# v029 with the 60 s_nop 0 M0-hazard pads before LDS-DMA loads removed by letting the address add sit between the M0 write and the load
# speedup vs baseline: 1.0023x; 1.0023x over previous
.LBB0_127:
	ds_read_b128 v[176:179], v167
	ds_read_b128 v[180:183], v167 offset:1024
	ds_read_b128 v[186:189], v167 offset:2048
	ds_read_b128 v[190:193], v167 offset:3072
	s_add_u32 s40, s38, 0xfff00080
	s_addc_u32 s41, s39, -1
	s_cmp_eq_u32 s54, 60
	s_cselect_b32 s43, s6, s41
	s_cselect_b32 s42, s7, s40
	s_cselect_b32 s41, s9, s29
	s_cselect_b32 s40, s11, s27
	v_lshl_add_u64 v[156:157], s[38:39], 0, v[138:139]
	s_add_i32 m0, s44, 0xc000
	ds_read_b128 v[194:197], v168
	ds_read_b128 v[198:201], v168 offset:1024
	ds_read_b128 v[202:205], v168 offset:2048
	ds_read_b128 v[206:209], v168 offset:3072
	ds_read_b128 v[210:213], v168 offset:4096
	ds_read_b128 v[214:217], v168 offset:5120
	ds_read_b128 v[218:221], v168 offset:6144
	ds_read_b128 v[222:225], v168 offset:7168
	global_load_lds_dwordx4 v[156:157], off
	s_add_i32 m0, s44, 0xe000
	v_lshl_add_u64 v[156:157], s[38:39], 0, v[140:141]
	global_load_lds_dwordx4 v[156:157], off
	s_waitcnt lgkmcnt(8)
	s_barrier
	s_waitcnt lgkmcnt(0)
	v_mfma_f32_16x16x32_bf16 v[124:127], v[176:179], v[194:197], v[124:127]
	v_mfma_f32_16x16x32_bf16 v[124:127], v[180:183], v[198:201], v[124:127]
	v_mfma_f32_16x16x32_bf16 v[120:123], v[186:189], v[194:197], v[120:123]
	v_mfma_f32_16x16x32_bf16 v[120:123], v[190:193], v[198:201], v[120:123]
	v_mfma_f32_16x16x32_bf16 v[108:111], v[176:179], v[202:205], v[108:111]
	v_mfma_f32_16x16x32_bf16 v[108:111], v[180:183], v[206:209], v[108:111]
	v_mfma_f32_16x16x32_bf16 v[104:107], v[186:189], v[202:205], v[104:107]
	v_mfma_f32_16x16x32_bf16 v[104:107], v[190:193], v[206:209], v[104:107]
	v_mfma_f32_16x16x32_bf16 v[92:95], v[176:179], v[210:213], v[92:95]
	v_mfma_f32_16x16x32_bf16 v[92:95], v[180:183], v[214:217], v[92:95]
	v_mfma_f32_16x16x32_bf16 v[88:91], v[186:189], v[210:213], v[88:91]
	v_mfma_f32_16x16x32_bf16 v[88:91], v[190:193], v[214:217], v[88:91]
	v_mfma_f32_16x16x32_bf16 v[76:79], v[176:179], v[218:221], v[76:79]
	v_mfma_f32_16x16x32_bf16 v[76:79], v[180:183], v[222:225], v[76:79]
	v_mfma_f32_16x16x32_bf16 v[72:75], v[186:189], v[218:221], v[72:75]
	v_mfma_f32_16x16x32_bf16 v[72:75], v[190:193], v[222:225], v[72:75]
	s_barrier
	s_add_i32 s55, s72, s5
	v_lshl_add_u64 v[156:157], s[40:41], 0, v[130:131]
	s_mov_b32 m0, s55
	ds_read_b128 v[226:229], v169
	ds_read_b128 v[230:233], v169 offset:1024
	ds_read_b128 v[234:237], v169 offset:2048
	ds_read_b128 v[238:241], v169 offset:3072
	global_load_lds_dwordx4 v[156:157], off
	s_add_i32 m0, s55, 0x2000
	v_lshl_add_u64 v[162:163], s[40:41], 0, v[134:135]
	global_load_lds_dwordx4 v[162:163], off
	s_barrier
	s_waitcnt lgkmcnt(0)
	v_mfma_f32_16x16x32_bf16 v[116:119], v[226:229], v[194:197], v[116:119]
	v_mfma_f32_16x16x32_bf16 v[116:119], v[230:233], v[198:201], v[116:119]
	v_mfma_f32_16x16x32_bf16 v[112:115], v[234:237], v[194:197], v[112:115]
	v_mfma_f32_16x16x32_bf16 v[112:115], v[238:241], v[198:201], v[112:115]
	v_mfma_f32_16x16x32_bf16 v[100:103], v[226:229], v[202:205], v[100:103]
	v_mfma_f32_16x16x32_bf16 v[100:103], v[230:233], v[206:209], v[100:103]
	v_mfma_f32_16x16x32_bf16 v[96:99], v[234:237], v[202:205], v[96:99]
	v_mfma_f32_16x16x32_bf16 v[96:99], v[238:241], v[206:209], v[96:99]
	v_mfma_f32_16x16x32_bf16 v[84:87], v[226:229], v[210:213], v[84:87]
	v_mfma_f32_16x16x32_bf16 v[84:87], v[230:233], v[214:217], v[84:87]
	v_mfma_f32_16x16x32_bf16 v[80:83], v[234:237], v[210:213], v[80:83]
	v_mfma_f32_16x16x32_bf16 v[80:83], v[238:241], v[214:217], v[80:83]
	v_mfma_f32_16x16x32_bf16 v[68:71], v[226:229], v[218:221], v[68:71]
	v_mfma_f32_16x16x32_bf16 v[68:71], v[230:233], v[222:225], v[68:71]
	v_mfma_f32_16x16x32_bf16 v[64:67], v[234:237], v[218:221], v[64:67]
	v_mfma_f32_16x16x32_bf16 v[64:67], v[238:241], v[222:225], v[64:67]
	s_mov_b32 m0, s44
	v_lshl_add_u64 v[170:171], s[42:43], 0, v[128:129]
	s_barrier
	ds_read_b128 v[194:197], v168 offset:16384
	ds_read_b128 v[198:201], v168 offset:17408
	ds_read_b128 v[202:205], v168 offset:18432
	ds_read_b128 v[206:209], v168 offset:19456
	ds_read_b128 v[210:213], v168 offset:20480
	ds_read_b128 v[214:217], v168 offset:21504
	ds_read_b128 v[218:221], v168 offset:22528
	ds_read_b128 v[222:225], v168 offset:23552
	global_load_lds_dwordx4 v[170:171], off
	s_mov_b32 m0, s45
	v_lshl_add_u64 v[242:243], s[42:43], 0, v[132:133]
	global_load_lds_dwordx4 v[242:243], off
	s_barrier
	s_waitcnt lgkmcnt(0)
	v_mfma_f32_16x16x32_bf16 v[60:63], v[176:179], v[194:197], v[60:63]
	v_mfma_f32_16x16x32_bf16 v[60:63], v[180:183], v[198:201], v[60:63]
	v_mfma_f32_16x16x32_bf16 v[56:59], v[186:189], v[194:197], v[56:59]
	v_mfma_f32_16x16x32_bf16 v[56:59], v[190:193], v[198:201], v[56:59]
	v_mfma_f32_16x16x32_bf16 v[44:47], v[176:179], v[202:205], v[44:47]
	v_mfma_f32_16x16x32_bf16 v[44:47], v[180:183], v[206:209], v[44:47]
	v_mfma_f32_16x16x32_bf16 v[40:43], v[186:189], v[202:205], v[40:43]
	v_mfma_f32_16x16x32_bf16 v[40:43], v[190:193], v[206:209], v[40:43]
	v_mfma_f32_16x16x32_bf16 v[28:31], v[176:179], v[210:213], v[28:31]
	v_mfma_f32_16x16x32_bf16 v[28:31], v[180:183], v[214:217], v[28:31]
	v_mfma_f32_16x16x32_bf16 v[24:27], v[186:189], v[210:213], v[24:27]
	v_mfma_f32_16x16x32_bf16 v[24:27], v[190:193], v[214:217], v[24:27]
	v_mfma_f32_16x16x32_bf16 v[12:15], v[176:179], v[218:221], v[12:15]
	v_mfma_f32_16x16x32_bf16 v[12:15], v[180:183], v[222:225], v[12:15]
	v_mfma_f32_16x16x32_bf16 v[8:11], v[186:189], v[218:221], v[8:11]
	v_mfma_f32_16x16x32_bf16 v[8:11], v[190:193], v[222:225], v[8:11]
	s_barrier
	s_add_u32 s62, s40, 0x100000
	s_addc_u32 s63, s41, 0
	s_add_i32 s55, s73, s5
	s_mov_b32 m0, s55
	v_lshl_add_u64 v[176:177], s[62:63], 0, v[130:131]
	global_load_lds_dwordx4 v[176:177], off
	s_add_i32 m0, s55, 0x2000
	v_lshl_add_u64 v[176:177], s[62:63], 0, v[134:135]
	global_load_lds_dwordx4 v[176:177], off
	s_waitcnt vmcnt(6)
	s_barrier
	v_mfma_f32_16x16x32_bf16 v[52:55], v[226:229], v[194:197], v[52:55]
	v_mfma_f32_16x16x32_bf16 v[52:55], v[230:233], v[198:201], v[52:55]
	v_mfma_f32_16x16x32_bf16 v[48:51], v[234:237], v[194:197], v[48:51]
	v_mfma_f32_16x16x32_bf16 v[48:51], v[238:241], v[198:201], v[48:51]
	v_mfma_f32_16x16x32_bf16 v[36:39], v[226:229], v[202:205], v[36:39]
	v_mfma_f32_16x16x32_bf16 v[36:39], v[230:233], v[206:209], v[36:39]
	v_mfma_f32_16x16x32_bf16 v[32:35], v[234:237], v[202:205], v[32:35]
	v_mfma_f32_16x16x32_bf16 v[32:35], v[238:241], v[206:209], v[32:35]
	v_mfma_f32_16x16x32_bf16 v[20:23], v[226:229], v[210:213], v[20:23]
	v_mfma_f32_16x16x32_bf16 v[20:23], v[230:233], v[214:217], v[20:23]
	v_mfma_f32_16x16x32_bf16 v[16:19], v[234:237], v[210:213], v[16:19]
	v_mfma_f32_16x16x32_bf16 v[16:19], v[238:241], v[214:217], v[16:19]
	v_mfma_f32_16x16x32_bf16 v[4:7], v[226:229], v[218:221], v[4:7]
	v_mfma_f32_16x16x32_bf16 v[4:7], v[230:233], v[222:225], v[4:7]
	v_mfma_f32_16x16x32_bf16 v[0:3], v[234:237], v[218:221], v[0:3]
	v_mfma_f32_16x16x32_bf16 v[0:3], v[238:241], v[222:225], v[0:3]
	s_add_i32 s55, 0, 0x18000
	v_add_u32_e32 v137, s55, v165
	s_barrier
	ds_read_b128 v[176:179], v137
	ds_read_b128 v[180:183], v137 offset:1024
	ds_read_b128 v[186:189], v137 offset:2048
	ds_read_b128 v[190:193], v137 offset:3072
	s_add_u32 s42, s42, 0x100000
	s_addc_u32 s43, s43, 0
	s_mov_b32 m0, s46
	v_lshl_add_u64 v[226:227], s[42:43], 0, v[128:129]
	ds_read_b128 v[194:197], v168 offset:32768
	ds_read_b128 v[198:201], v168 offset:33792
	ds_read_b128 v[202:205], v168 offset:34816
	ds_read_b128 v[206:209], v168 offset:35840
	ds_read_b128 v[210:213], v168 offset:36864
	ds_read_b128 v[214:217], v168 offset:37888
	ds_read_b128 v[218:221], v168 offset:38912
	ds_read_b128 v[222:225], v168 offset:39936
	global_load_lds_dwordx4 v[226:227], off
	s_mov_b32 m0, s47
	v_lshl_add_u64 v[226:227], s[42:43], 0, v[132:133]
	global_load_lds_dwordx4 v[226:227], off
	s_waitcnt lgkmcnt(8)
	s_barrier
	s_waitcnt lgkmcnt(0)
	v_mfma_f32_16x16x32_bf16 v[124:127], v[176:179], v[194:197], v[124:127]
	v_mfma_f32_16x16x32_bf16 v[124:127], v[180:183], v[198:201], v[124:127]
	v_mfma_f32_16x16x32_bf16 v[120:123], v[186:189], v[194:197], v[120:123]
	v_mfma_f32_16x16x32_bf16 v[120:123], v[190:193], v[198:201], v[120:123]
	v_mfma_f32_16x16x32_bf16 v[108:111], v[176:179], v[202:205], v[108:111]
	v_mfma_f32_16x16x32_bf16 v[108:111], v[180:183], v[206:209], v[108:111]
	v_mfma_f32_16x16x32_bf16 v[104:107], v[186:189], v[202:205], v[104:107]
	v_mfma_f32_16x16x32_bf16 v[104:107], v[190:193], v[206:209], v[104:107]
	v_mfma_f32_16x16x32_bf16 v[92:95], v[176:179], v[210:213], v[92:95]
	v_mfma_f32_16x16x32_bf16 v[92:95], v[180:183], v[214:217], v[92:95]
	v_mfma_f32_16x16x32_bf16 v[88:91], v[186:189], v[210:213], v[88:91]
	v_mfma_f32_16x16x32_bf16 v[88:91], v[190:193], v[214:217], v[88:91]
	v_mfma_f32_16x16x32_bf16 v[76:79], v[176:179], v[218:221], v[76:79]
	v_mfma_f32_16x16x32_bf16 v[76:79], v[180:183], v[222:225], v[76:79]
	v_mfma_f32_16x16x32_bf16 v[72:75], v[186:189], v[218:221], v[72:75]
	v_mfma_f32_16x16x32_bf16 v[72:75], v[190:193], v[222:225], v[72:75]
	s_barrier
	s_add_i32 s42, 0, 0x1c000
	s_add_i32 s43, s55, s5
	v_add_u32_e32 v137, s42, v165
	v_lshl_add_u64 v[156:157], v[156:157], 0, s[24:25]
	s_mov_b32 m0, s43
	ds_read_b128 v[226:229], v137
	ds_read_b128 v[230:233], v137 offset:1024
	ds_read_b128 v[234:237], v137 offset:2048
	ds_read_b128 v[238:241], v137 offset:3072
	global_load_lds_dwordx4 v[156:157], off
	s_add_i32 m0, s43, 0x2000
	v_lshl_add_u64 v[156:157], v[162:163], 0, s[24:25]
	global_load_lds_dwordx4 v[156:157], off
	s_barrier
	s_waitcnt lgkmcnt(0)
	v_mfma_f32_16x16x32_bf16 v[116:119], v[226:229], v[194:197], v[116:119]
	v_mfma_f32_16x16x32_bf16 v[116:119], v[230:233], v[198:201], v[116:119]
	v_mfma_f32_16x16x32_bf16 v[112:115], v[234:237], v[194:197], v[112:115]
	v_mfma_f32_16x16x32_bf16 v[112:115], v[238:241], v[198:201], v[112:115]
	v_mfma_f32_16x16x32_bf16 v[100:103], v[226:229], v[202:205], v[100:103]
	v_mfma_f32_16x16x32_bf16 v[100:103], v[230:233], v[206:209], v[100:103]
	v_mfma_f32_16x16x32_bf16 v[96:99], v[234:237], v[202:205], v[96:99]
	v_mfma_f32_16x16x32_bf16 v[96:99], v[238:241], v[206:209], v[96:99]
	v_mfma_f32_16x16x32_bf16 v[84:87], v[226:229], v[210:213], v[84:87]
	v_mfma_f32_16x16x32_bf16 v[84:87], v[230:233], v[214:217], v[84:87]
	v_mfma_f32_16x16x32_bf16 v[80:83], v[234:237], v[210:213], v[80:83]
	v_mfma_f32_16x16x32_bf16 v[80:83], v[238:241], v[214:217], v[80:83]
	v_mfma_f32_16x16x32_bf16 v[68:71], v[226:229], v[218:221], v[68:71]
	v_mfma_f32_16x16x32_bf16 v[68:71], v[230:233], v[222:225], v[68:71]
	v_mfma_f32_16x16x32_bf16 v[64:67], v[234:237], v[218:221], v[64:67]
	v_mfma_f32_16x16x32_bf16 v[64:67], v[238:241], v[222:225], v[64:67]
	s_mov_b32 m0, s49
	v_lshl_add_u64 v[156:157], v[170:171], 0, s[24:25]
	s_barrier
	ds_read_b128 v[194:197], v168 offset:49152
	ds_read_b128 v[198:201], v168 offset:50176
	ds_read_b128 v[202:205], v168 offset:51200
	ds_read_b128 v[206:209], v168 offset:52224
	ds_read_b128 v[210:213], v168 offset:53248
	ds_read_b128 v[214:217], v168 offset:54272
	ds_read_b128 v[218:221], v168 offset:55296
	ds_read_b128 v[222:225], v168 offset:56320
	global_load_lds_dwordx4 v[156:157], off
	s_mov_b32 m0, s50
	v_lshl_add_u64 v[156:157], v[242:243], 0, s[24:25]
	global_load_lds_dwordx4 v[156:157], off
	s_barrier
	s_waitcnt lgkmcnt(0)
	v_mfma_f32_16x16x32_bf16 v[60:63], v[176:179], v[194:197], v[60:63]
	v_mfma_f32_16x16x32_bf16 v[60:63], v[180:183], v[198:201], v[60:63]
	v_mfma_f32_16x16x32_bf16 v[56:59], v[186:189], v[194:197], v[56:59]
	v_mfma_f32_16x16x32_bf16 v[56:59], v[190:193], v[198:201], v[56:59]
	v_mfma_f32_16x16x32_bf16 v[44:47], v[176:179], v[202:205], v[44:47]
	v_mfma_f32_16x16x32_bf16 v[44:47], v[180:183], v[206:209], v[44:47]
	v_mfma_f32_16x16x32_bf16 v[40:43], v[186:189], v[202:205], v[40:43]
	v_mfma_f32_16x16x32_bf16 v[40:43], v[190:193], v[206:209], v[40:43]
	v_mfma_f32_16x16x32_bf16 v[28:31], v[176:179], v[210:213], v[28:31]
	v_mfma_f32_16x16x32_bf16 v[28:31], v[180:183], v[214:217], v[28:31]
	v_mfma_f32_16x16x32_bf16 v[24:27], v[186:189], v[210:213], v[24:27]
	v_mfma_f32_16x16x32_bf16 v[24:27], v[190:193], v[214:217], v[24:27]
	v_mfma_f32_16x16x32_bf16 v[12:15], v[176:179], v[218:221], v[12:15]
	v_mfma_f32_16x16x32_bf16 v[12:15], v[180:183], v[222:225], v[12:15]
	v_mfma_f32_16x16x32_bf16 v[8:11], v[186:189], v[218:221], v[8:11]
	v_mfma_f32_16x16x32_bf16 v[8:11], v[190:193], v[222:225], v[8:11]
	s_barrier
	s_add_u32 s40, s40, 0x100080
	s_addc_u32 s41, s41, 0
	s_add_i32 s42, s42, s5
	s_mov_b32 m0, s42
	v_lshl_add_u64 v[156:157], s[40:41], 0, v[130:131]
	global_load_lds_dwordx4 v[156:157], off
	s_add_i32 m0, s42, 0x2000
	v_lshl_add_u64 v[156:157], s[40:41], 0, v[134:135]
	global_load_lds_dwordx4 v[156:157], off
	s_waitcnt vmcnt(6)
	s_barrier
	v_mfma_f32_16x16x32_bf16 v[52:55], v[226:229], v[194:197], v[52:55]
	v_mfma_f32_16x16x32_bf16 v[52:55], v[230:233], v[198:201], v[52:55]
	v_mfma_f32_16x16x32_bf16 v[48:51], v[234:237], v[194:197], v[48:51]
	v_mfma_f32_16x16x32_bf16 v[48:51], v[238:241], v[198:201], v[48:51]
	v_mfma_f32_16x16x32_bf16 v[36:39], v[226:229], v[202:205], v[36:39]
	v_mfma_f32_16x16x32_bf16 v[36:39], v[230:233], v[206:209], v[36:39]
	v_mfma_f32_16x16x32_bf16 v[32:35], v[234:237], v[202:205], v[32:35]
	v_mfma_f32_16x16x32_bf16 v[32:35], v[238:241], v[206:209], v[32:35]
	v_mfma_f32_16x16x32_bf16 v[20:23], v[226:229], v[210:213], v[20:23]
	v_mfma_f32_16x16x32_bf16 v[20:23], v[230:233], v[214:217], v[20:23]
	v_mfma_f32_16x16x32_bf16 v[16:19], v[234:237], v[210:213], v[16:19]
	v_mfma_f32_16x16x32_bf16 v[16:19], v[238:241], v[214:217], v[16:19]
	v_mfma_f32_16x16x32_bf16 v[4:7], v[226:229], v[218:221], v[4:7]
	v_mfma_f32_16x16x32_bf16 v[4:7], v[230:233], v[222:225], v[4:7]
	v_mfma_f32_16x16x32_bf16 v[0:3], v[234:237], v[218:221], v[0:3]
	v_mfma_f32_16x16x32_bf16 v[0:3], v[238:241], v[222:225], v[0:3]
	s_add_i32 s54, s54, 2
	s_add_u32 s38, s38, 0x100
	s_addc_u32 s39, s39, 0
	s_add_u32 s27, s27, 0x100
	s_addc_u32 s29, s29, 0
	s_cmp_gt_u32 s54, 61
	s_barrier
	s_cbranch_scc0 .LBB0_127
	v_lshl_or_b32 v156, s8, 8, v166
	s_waitcnt vmcnt(0)
	v_pk_mul_f32 v[126:127], v[160:161], v[126:127] op_sel_hi:[0,1]
	v_pk_mul_f32 v[124:125], v[160:161], v[124:125] op_sel_hi:[0,1]
	v_pk_mul_f32 v[122:123], v[160:161], v[122:123] op_sel_hi:[0,1]
	v_pk_mul_f32 v[162:163], v[160:161], v[120:121] op_sel_hi:[0,1]
	v_cmp_lt_i32_e64 s[8:9], s74, v156
	s_and_saveexec_b64 s[38:39], s[8:9]
	s_cbranch_execz .LBB0_130
	v_mul_f32_e32 v147, 0xbfb8aa3b, v126
	v_mul_f32_e32 v121, 0xbfb8aa3b, v162
	v_exp_f32_e32 v147, v147
	v_mul_f32_e32 v149, 0xbfb8aa3b, v122
	v_mul_f32_e32 v137, 0xbfb8aa3b, v125
	v_exp_f32_e32 v121, v121
	v_exp_f32_e32 v149, v149
	v_exp_f32_e32 v137, v137
	v_add_f32_e32 v147, 1.0, v147
	v_add_f32_e32 v121, 1.0, v121
	v_rcp_f32_e32 v176, v147
	v_add_f32_e32 v147, 1.0, v149
	v_mul_f32_e32 v149, 0xbfb8aa3b, v127
	v_mul_f32_e32 v120, 0xbfb8aa3b, v124
	v_rcp_f32_e32 v170, v121
	v_add_f32_e32 v121, 1.0, v137
	v_mul_f32_e32 v137, 0xbfb8aa3b, v163
	v_exp_f32_e32 v149, v149
	v_mul_f32_e32 v151, 0xbfb8aa3b, v123
	v_exp_f32_e32 v120, v120
	v_exp_f32_e32 v137, v137
	v_exp_f32_e32 v151, v151
	v_rcp_f32_e32 v178, v147
	v_add_f32_e32 v147, 1.0, v149
	v_add_f32_e32 v120, 1.0, v120
	v_add_f32_e32 v137, 1.0, v137
	v_rcp_f32_e32 v177, v147
	v_add_f32_e32 v147, 1.0, v151
	v_rcp_f32_e32 v120, v120
	v_rcp_f32_e32 v121, v121
	v_rcp_f32_e32 v179, v147
	v_rcp_f32_e32 v171, v137
	v_pk_mul_f32 v[126:127], v[126:127], v[176:177]
	v_pk_mul_f32 v[124:125], v[124:125], v[120:121]
	v_pk_mul_f32 v[122:123], v[122:123], v[178:179]
	v_pk_mul_f32 v[162:163], v[162:163], v[170:171]

.LBB0_301:
	ds_read_b128 v[160:163], v151
	ds_read_b128 v[164:167], v151 offset:1024
	ds_read_b128 v[168:171], v151 offset:2048
	ds_read_b128 v[176:179], v151 offset:3072
	s_add_u32 s44, s42, 0x100
	s_addc_u32 s45, s43, 0
	s_cmp_eq_u32 s83, 12
	s_cselect_b32 s49, s39, s45
	s_cselect_b32 s48, s38, s44
	s_cselect_b32 s47, s37, s82
	s_cselect_b32 s46, s62, s63
	v_lshl_add_u64 v[214:215], s[42:43], 0, v[142:143]
	s_add_i32 m0, s50, 0xc000
	ds_read_b128 v[180:183], v153
	ds_read_b128 v[186:189], v153 offset:1024
	ds_read_b128 v[190:193], v153 offset:2048
	ds_read_b128 v[194:197], v153 offset:3072
	ds_read_b128 v[198:201], v153 offset:4096
	ds_read_b128 v[202:205], v153 offset:5120
	ds_read_b128 v[206:209], v153 offset:6144
	ds_read_b128 v[210:213], v153 offset:7168
	global_load_lds_dwordx4 v[214:215], off
	s_add_i32 m0, s50, 0xe000
	v_lshl_add_u64 v[214:215], s[42:43], 0, v[144:145]
	global_load_lds_dwordx4 v[214:215], off
	s_waitcnt lgkmcnt(8)
	s_barrier
	s_waitcnt lgkmcnt(0)
	v_mfma_f32_16x16x32_bf16 v[124:127], v[160:163], v[180:183], v[124:127]
	v_mfma_f32_16x16x32_bf16 v[124:127], v[164:167], v[186:189], v[124:127]
	v_mfma_f32_16x16x32_bf16 v[120:123], v[168:171], v[180:183], v[120:123]
	v_mfma_f32_16x16x32_bf16 v[120:123], v[176:179], v[186:189], v[120:123]
	v_mfma_f32_16x16x32_bf16 v[112:115], v[160:163], v[190:193], v[112:115]
	v_mfma_f32_16x16x32_bf16 v[112:115], v[164:167], v[194:197], v[112:115]
	v_mfma_f32_16x16x32_bf16 v[104:107], v[168:171], v[190:193], v[104:107]
	v_mfma_f32_16x16x32_bf16 v[104:107], v[176:179], v[194:197], v[104:107]
	v_mfma_f32_16x16x32_bf16 v[96:99], v[160:163], v[198:201], v[96:99]
	v_mfma_f32_16x16x32_bf16 v[96:99], v[164:167], v[202:205], v[96:99]
	v_mfma_f32_16x16x32_bf16 v[88:91], v[168:171], v[198:201], v[88:91]
	v_mfma_f32_16x16x32_bf16 v[88:91], v[176:179], v[202:205], v[88:91]
	v_mfma_f32_16x16x32_bf16 v[80:83], v[160:163], v[206:209], v[80:83]
	v_mfma_f32_16x16x32_bf16 v[80:83], v[164:167], v[210:213], v[80:83]
	v_mfma_f32_16x16x32_bf16 v[72:75], v[168:171], v[206:209], v[72:75]
	v_mfma_f32_16x16x32_bf16 v[72:75], v[176:179], v[210:213], v[72:75]
	s_barrier
	s_add_i32 s42, s76, s5
	v_lshl_add_u64 v[230:231], s[46:47], 0, v[132:133]
	s_mov_b32 m0, s42
	ds_read_b128 v[214:217], v155
	ds_read_b128 v[218:221], v155 offset:1024
	ds_read_b128 v[222:225], v155 offset:2048
	ds_read_b128 v[226:229], v155 offset:3072
	global_load_lds_dwordx4 v[230:231], off
	s_add_i32 m0, s42, 0x2000
	v_lshl_add_u64 v[232:233], s[46:47], 0, v[128:129]
	global_load_lds_dwordx4 v[232:233], off
	s_barrier
	s_waitcnt lgkmcnt(0)
	v_mfma_f32_16x16x32_bf16 v[116:119], v[214:217], v[180:183], v[116:119]
	v_mfma_f32_16x16x32_bf16 v[116:119], v[218:221], v[186:189], v[116:119]
	v_mfma_f32_16x16x32_bf16 v[108:111], v[222:225], v[180:183], v[108:111]
	v_mfma_f32_16x16x32_bf16 v[108:111], v[226:229], v[186:189], v[108:111]
	v_mfma_f32_16x16x32_bf16 v[100:103], v[214:217], v[190:193], v[100:103]
	v_mfma_f32_16x16x32_bf16 v[100:103], v[218:221], v[194:197], v[100:103]
	v_mfma_f32_16x16x32_bf16 v[92:95], v[222:225], v[190:193], v[92:95]
	v_mfma_f32_16x16x32_bf16 v[92:95], v[226:229], v[194:197], v[92:95]
	v_mfma_f32_16x16x32_bf16 v[84:87], v[214:217], v[198:201], v[84:87]
	v_mfma_f32_16x16x32_bf16 v[84:87], v[218:221], v[202:205], v[84:87]
	v_mfma_f32_16x16x32_bf16 v[76:79], v[222:225], v[198:201], v[76:79]
	v_mfma_f32_16x16x32_bf16 v[76:79], v[226:229], v[202:205], v[76:79]
	v_mfma_f32_16x16x32_bf16 v[68:71], v[214:217], v[206:209], v[68:71]
	v_mfma_f32_16x16x32_bf16 v[68:71], v[218:221], v[210:213], v[68:71]
	v_mfma_f32_16x16x32_bf16 v[64:67], v[222:225], v[206:209], v[64:67]
	v_mfma_f32_16x16x32_bf16 v[64:67], v[226:229], v[210:213], v[64:67]
	s_mov_b32 m0, s50
	v_lshl_add_u64 v[234:235], s[48:49], 0, v[134:135]
	s_barrier
	ds_read_b128 v[180:183], v153 offset:16384
	ds_read_b128 v[186:189], v153 offset:17408
	ds_read_b128 v[190:193], v153 offset:18432
	ds_read_b128 v[194:197], v153 offset:19456
	ds_read_b128 v[198:201], v153 offset:20480
	ds_read_b128 v[202:205], v153 offset:21504
	ds_read_b128 v[206:209], v153 offset:22528
	ds_read_b128 v[210:213], v153 offset:23552
	global_load_lds_dwordx4 v[234:235], off
	s_mov_b32 m0, s51
	v_lshl_add_u64 v[236:237], s[48:49], 0, v[130:131]
	global_load_lds_dwordx4 v[236:237], off
	s_barrier
	s_waitcnt lgkmcnt(0)
	v_mfma_f32_16x16x32_bf16 v[60:63], v[160:163], v[180:183], v[60:63]
	v_mfma_f32_16x16x32_bf16 v[60:63], v[164:167], v[186:189], v[60:63]
	v_mfma_f32_16x16x32_bf16 v[56:59], v[168:171], v[180:183], v[56:59]
	v_mfma_f32_16x16x32_bf16 v[56:59], v[176:179], v[186:189], v[56:59]
	v_mfma_f32_16x16x32_bf16 v[48:51], v[160:163], v[190:193], v[48:51]
	v_mfma_f32_16x16x32_bf16 v[48:51], v[164:167], v[194:197], v[48:51]
	v_mfma_f32_16x16x32_bf16 v[40:43], v[168:171], v[190:193], v[40:43]
	v_mfma_f32_16x16x32_bf16 v[40:43], v[176:179], v[194:197], v[40:43]
	v_mfma_f32_16x16x32_bf16 v[32:35], v[160:163], v[198:201], v[32:35]
	v_mfma_f32_16x16x32_bf16 v[32:35], v[164:167], v[202:205], v[32:35]
	v_mfma_f32_16x16x32_bf16 v[24:27], v[168:171], v[198:201], v[24:27]
	v_mfma_f32_16x16x32_bf16 v[24:27], v[176:179], v[202:205], v[24:27]
	v_mfma_f32_16x16x32_bf16 v[16:19], v[160:163], v[206:209], v[16:19]
	v_mfma_f32_16x16x32_bf16 v[16:19], v[164:167], v[210:213], v[16:19]
	v_mfma_f32_16x16x32_bf16 v[8:11], v[168:171], v[206:209], v[8:11]
	v_mfma_f32_16x16x32_bf16 v[8:11], v[176:179], v[210:213], v[8:11]
	s_barrier
	s_add_u32 s42, s46, 0x40000
	s_addc_u32 s43, s47, 0
	s_add_i32 s84, s77, s5
	s_mov_b32 m0, s84
	v_lshl_add_u64 v[160:161], s[42:43], 0, v[132:133]
	global_load_lds_dwordx4 v[160:161], off
	s_add_i32 m0, s84, 0x2000
	v_lshl_add_u64 v[160:161], s[42:43], 0, v[128:129]
	global_load_lds_dwordx4 v[160:161], off
	s_waitcnt vmcnt(6)
	s_barrier
	v_mfma_f32_16x16x32_bf16 v[52:55], v[214:217], v[180:183], v[52:55]
	v_mfma_f32_16x16x32_bf16 v[52:55], v[218:221], v[186:189], v[52:55]
	v_mfma_f32_16x16x32_bf16 v[44:47], v[222:225], v[180:183], v[44:47]
	v_mfma_f32_16x16x32_bf16 v[44:47], v[226:229], v[186:189], v[44:47]
	v_mfma_f32_16x16x32_bf16 v[36:39], v[214:217], v[190:193], v[36:39]
	v_mfma_f32_16x16x32_bf16 v[36:39], v[218:221], v[194:197], v[36:39]
	v_mfma_f32_16x16x32_bf16 v[28:31], v[222:225], v[190:193], v[28:31]
	v_mfma_f32_16x16x32_bf16 v[28:31], v[226:229], v[194:197], v[28:31]
	v_mfma_f32_16x16x32_bf16 v[20:23], v[214:217], v[198:201], v[20:23]
	v_mfma_f32_16x16x32_bf16 v[20:23], v[218:221], v[202:205], v[20:23]
	v_mfma_f32_16x16x32_bf16 v[12:15], v[222:225], v[198:201], v[12:15]
	v_mfma_f32_16x16x32_bf16 v[12:15], v[226:229], v[202:205], v[12:15]
	v_mfma_f32_16x16x32_bf16 v[4:7], v[214:217], v[206:209], v[4:7]
	v_mfma_f32_16x16x32_bf16 v[4:7], v[218:221], v[210:213], v[4:7]
	v_mfma_f32_16x16x32_bf16 v[0:3], v[222:225], v[206:209], v[0:3]
	v_mfma_f32_16x16x32_bf16 v[0:3], v[226:229], v[210:213], v[0:3]
	s_add_i32 s84, 0, 0x18000
	v_add_u32_e32 v157, s84, v139
	s_barrier
	ds_read_b128 v[160:163], v157
	ds_read_b128 v[164:167], v157 offset:1024
	ds_read_b128 v[168:171], v157 offset:2048
	ds_read_b128 v[176:179], v157 offset:3072
	s_add_u32 s42, s48, 0x170000
	s_addc_u32 s43, s49, 0
	s_mov_b32 m0, s52
	v_lshl_add_u64 v[214:215], s[42:43], 0, v[134:135]
	ds_read_b128 v[180:183], v153 offset:32768
	ds_read_b128 v[186:189], v153 offset:33792
	ds_read_b128 v[190:193], v153 offset:34816
	ds_read_b128 v[194:197], v153 offset:35840
	ds_read_b128 v[198:201], v153 offset:36864
	ds_read_b128 v[202:205], v153 offset:37888
	ds_read_b128 v[206:209], v153 offset:38912
	ds_read_b128 v[210:213], v153 offset:39936
	global_load_lds_dwordx4 v[214:215], off
	s_mov_b32 m0, s53
	v_lshl_add_u64 v[214:215], s[42:43], 0, v[130:131]
	global_load_lds_dwordx4 v[214:215], off
	s_waitcnt lgkmcnt(8)
	s_barrier
	s_waitcnt lgkmcnt(0)
	v_mfma_f32_16x16x32_bf16 v[124:127], v[160:163], v[180:183], v[124:127]
	v_mfma_f32_16x16x32_bf16 v[124:127], v[164:167], v[186:189], v[124:127]
	v_mfma_f32_16x16x32_bf16 v[120:123], v[168:171], v[180:183], v[120:123]
	v_mfma_f32_16x16x32_bf16 v[120:123], v[176:179], v[186:189], v[120:123]
	v_mfma_f32_16x16x32_bf16 v[112:115], v[160:163], v[190:193], v[112:115]
	v_mfma_f32_16x16x32_bf16 v[112:115], v[164:167], v[194:197], v[112:115]
	v_mfma_f32_16x16x32_bf16 v[104:107], v[168:171], v[190:193], v[104:107]
	v_mfma_f32_16x16x32_bf16 v[104:107], v[176:179], v[194:197], v[104:107]
	v_mfma_f32_16x16x32_bf16 v[96:99], v[160:163], v[198:201], v[96:99]
	v_mfma_f32_16x16x32_bf16 v[96:99], v[164:167], v[202:205], v[96:99]
	v_mfma_f32_16x16x32_bf16 v[88:91], v[168:171], v[198:201], v[88:91]
	v_mfma_f32_16x16x32_bf16 v[88:91], v[176:179], v[202:205], v[88:91]
	v_mfma_f32_16x16x32_bf16 v[80:83], v[160:163], v[206:209], v[80:83]
	v_mfma_f32_16x16x32_bf16 v[80:83], v[164:167], v[210:213], v[80:83]
	v_mfma_f32_16x16x32_bf16 v[72:75], v[168:171], v[206:209], v[72:75]
	v_mfma_f32_16x16x32_bf16 v[72:75], v[176:179], v[210:213], v[72:75]
	s_barrier
	s_add_i32 s48, 0, 0x1c000
	s_add_i32 s42, s84, s5
	v_add_u32_e32 v157, s48, v139
	v_lshl_add_u64 v[230:231], v[230:231], 0, s[10:11]
	s_mov_b32 m0, s42
	ds_read_b128 v[214:217], v157
	ds_read_b128 v[218:221], v157 offset:1024
	ds_read_b128 v[222:225], v157 offset:2048
	ds_read_b128 v[226:229], v157 offset:3072
	global_load_lds_dwordx4 v[230:231], off
	s_add_i32 m0, s42, 0x2000
	v_lshl_add_u64 v[230:231], v[232:233], 0, s[10:11]
	global_load_lds_dwordx4 v[230:231], off
	s_barrier
	s_waitcnt lgkmcnt(0)
	v_mfma_f32_16x16x32_bf16 v[116:119], v[214:217], v[180:183], v[116:119]
	v_mfma_f32_16x16x32_bf16 v[116:119], v[218:221], v[186:189], v[116:119]
	v_mfma_f32_16x16x32_bf16 v[108:111], v[222:225], v[180:183], v[108:111]
	v_mfma_f32_16x16x32_bf16 v[108:111], v[226:229], v[186:189], v[108:111]
	v_mfma_f32_16x16x32_bf16 v[100:103], v[214:217], v[190:193], v[100:103]
	v_mfma_f32_16x16x32_bf16 v[100:103], v[218:221], v[194:197], v[100:103]
	v_mfma_f32_16x16x32_bf16 v[92:95], v[222:225], v[190:193], v[92:95]
	v_mfma_f32_16x16x32_bf16 v[92:95], v[226:229], v[194:197], v[92:95]
	v_mfma_f32_16x16x32_bf16 v[84:87], v[214:217], v[198:201], v[84:87]
	v_mfma_f32_16x16x32_bf16 v[84:87], v[218:221], v[202:205], v[84:87]
	v_mfma_f32_16x16x32_bf16 v[76:79], v[222:225], v[198:201], v[76:79]
	v_mfma_f32_16x16x32_bf16 v[76:79], v[226:229], v[202:205], v[76:79]
	v_mfma_f32_16x16x32_bf16 v[68:71], v[214:217], v[206:209], v[68:71]
	v_mfma_f32_16x16x32_bf16 v[68:71], v[218:221], v[210:213], v[68:71]
	v_mfma_f32_16x16x32_bf16 v[64:67], v[222:225], v[206:209], v[64:67]
	v_mfma_f32_16x16x32_bf16 v[64:67], v[226:229], v[210:213], v[64:67]
	s_mov_b32 m0, s55
	v_lshl_add_u64 v[230:231], v[234:235], 0, s[10:11]
	s_barrier
	ds_read_b128 v[180:183], v153 offset:49152
	ds_read_b128 v[186:189], v153 offset:50176
	ds_read_b128 v[190:193], v153 offset:51200
	ds_read_b128 v[194:197], v153 offset:52224
	ds_read_b128 v[198:201], v153 offset:53248
	ds_read_b128 v[202:205], v153 offset:54272
	ds_read_b128 v[206:209], v153 offset:55296
	ds_read_b128 v[210:213], v153 offset:56320
	global_load_lds_dwordx4 v[230:231], off
	s_mov_b32 m0, s61
	v_lshl_add_u64 v[230:231], v[236:237], 0, s[10:11]
	global_load_lds_dwordx4 v[230:231], off
	s_barrier
	s_waitcnt lgkmcnt(0)
	v_mfma_f32_16x16x32_bf16 v[60:63], v[160:163], v[180:183], v[60:63]
	v_mfma_f32_16x16x32_bf16 v[60:63], v[164:167], v[186:189], v[60:63]
	v_mfma_f32_16x16x32_bf16 v[56:59], v[168:171], v[180:183], v[56:59]
	v_mfma_f32_16x16x32_bf16 v[56:59], v[176:179], v[186:189], v[56:59]
	v_mfma_f32_16x16x32_bf16 v[48:51], v[160:163], v[190:193], v[48:51]
	v_mfma_f32_16x16x32_bf16 v[48:51], v[164:167], v[194:197], v[48:51]
	v_mfma_f32_16x16x32_bf16 v[40:43], v[168:171], v[190:193], v[40:43]
	v_mfma_f32_16x16x32_bf16 v[40:43], v[176:179], v[194:197], v[40:43]
	v_mfma_f32_16x16x32_bf16 v[32:35], v[160:163], v[198:201], v[32:35]
	v_mfma_f32_16x16x32_bf16 v[32:35], v[164:167], v[202:205], v[32:35]
	v_mfma_f32_16x16x32_bf16 v[24:27], v[168:171], v[198:201], v[24:27]
	v_mfma_f32_16x16x32_bf16 v[24:27], v[176:179], v[202:205], v[24:27]
	v_mfma_f32_16x16x32_bf16 v[16:19], v[160:163], v[206:209], v[16:19]
	v_mfma_f32_16x16x32_bf16 v[16:19], v[164:167], v[210:213], v[16:19]
	v_mfma_f32_16x16x32_bf16 v[8:11], v[168:171], v[206:209], v[8:11]
	v_mfma_f32_16x16x32_bf16 v[8:11], v[176:179], v[210:213], v[8:11]
	s_barrier
	s_add_u32 s42, s46, 0x40080
	s_addc_u32 s43, s47, 0
	s_add_i32 s46, s48, s5
	s_mov_b32 m0, s46
	v_lshl_add_u64 v[160:161], s[42:43], 0, v[132:133]
	global_load_lds_dwordx4 v[160:161], off
	s_add_i32 m0, s46, 0x2000
	v_lshl_add_u64 v[160:161], s[42:43], 0, v[128:129]
	global_load_lds_dwordx4 v[160:161], off
	s_waitcnt vmcnt(6)
	s_barrier
	v_mfma_f32_16x16x32_bf16 v[52:55], v[214:217], v[180:183], v[52:55]
	v_mfma_f32_16x16x32_bf16 v[52:55], v[218:221], v[186:189], v[52:55]
	v_mfma_f32_16x16x32_bf16 v[44:47], v[222:225], v[180:183], v[44:47]
	v_mfma_f32_16x16x32_bf16 v[44:47], v[226:229], v[186:189], v[44:47]
	v_mfma_f32_16x16x32_bf16 v[36:39], v[214:217], v[190:193], v[36:39]
	v_mfma_f32_16x16x32_bf16 v[36:39], v[218:221], v[194:197], v[36:39]
	v_mfma_f32_16x16x32_bf16 v[28:31], v[222:225], v[190:193], v[28:31]
	v_mfma_f32_16x16x32_bf16 v[28:31], v[226:229], v[194:197], v[28:31]
	v_mfma_f32_16x16x32_bf16 v[20:23], v[214:217], v[198:201], v[20:23]
	v_mfma_f32_16x16x32_bf16 v[20:23], v[218:221], v[202:205], v[20:23]
	v_mfma_f32_16x16x32_bf16 v[12:15], v[222:225], v[198:201], v[12:15]
	v_mfma_f32_16x16x32_bf16 v[12:15], v[226:229], v[202:205], v[12:15]
	v_mfma_f32_16x16x32_bf16 v[4:7], v[214:217], v[206:209], v[4:7]
	v_mfma_f32_16x16x32_bf16 v[4:7], v[218:221], v[210:213], v[4:7]
	v_mfma_f32_16x16x32_bf16 v[0:3], v[222:225], v[206:209], v[0:3]
	v_mfma_f32_16x16x32_bf16 v[0:3], v[226:229], v[210:213], v[0:3]
	s_add_i32 s83, s83, 2
	s_add_u32 s63, s63, 0x100
	s_addc_u32 s82, s82, 0
	s_cmp_gt_u32 s83, 13
	s_mov_b64 s[42:43], s[44:45]
	s_barrier
	s_cbranch_scc0 .LBB0_301
	v_lshl_or_b32 v162, s81, 8, v141
	v_lshl_add_u32 v157, s80, 8, v137
	v_ashrrev_i32_e32 v163, 31, v162
	v_mov_b64_e32 v[160:161], s[12:13]
	v_mad_i64_i32 v[164:165], s[42:43], v157, s78, v[160:161]
	v_lshlrev_b64 v[162:163], 1, v[162:163]
	v_lshl_add_u64 v[164:165], v[164:165], 0, v[162:163]
	s_waitcnt vmcnt(0)
	v_pk_mul_f32 v[126:127], v[158:159], v[126:127] op_sel_hi:[0,1]
	v_pk_mul_f32 v[124:125], v[158:159], v[124:125] op_sel_hi:[0,1]
	v_pk_mul_f32 v[166:167], v[158:159], v[122:123] op_sel_hi:[0,1]
	v_pk_mul_f32 v[122:123], v[158:159], v[120:121] op_sel_hi:[0,1]
	v_cvt_pk_bf16_f32 v120, v124, v125
	v_cvt_pk_bf16_f32 v121, v126, v127
	v_cvt_pk_bf16_f32 v122, v122, v123
	v_cvt_pk_bf16_f32 v123, v166, v167
	global_store_dwordx4 v[164:165], v[120:123], off
	v_pk_mul_f32 v[116:117], v[158:159], v[116:117] op_sel_hi:[0,1]
	v_pk_mul_f32 v[118:119], v[158:159], v[118:119] op_sel_hi:[0,1]
	v_pk_mul_f32 v[120:121], v[158:159], v[110:111] op_sel_hi:[0,1]
	v_pk_mul_f32 v[110:111], v[158:159], v[108:109] op_sel_hi:[0,1]
	v_cvt_pk_bf16_f32 v108, v116, v117
	v_cvt_pk_bf16_f32 v109, v118, v119
	v_cvt_pk_bf16_f32 v110, v110, v111
	v_cvt_pk_bf16_f32 v111, v120, v121
	global_store_dwordx4 v[164:165], v[108:111], off offset:256
	v_pk_mul_f32 v[112:113], v[156:157], v[112:113] op_sel_hi:[0,1]
	v_pk_mul_f32 v[100:101], v[156:157], v[100:101] op_sel_hi:[0,1]
	v_or_b32_e32 v108, 16, v157
	v_mad_i64_i32 v[108:109], s[42:43], v108, s78, v[160:161]
	v_lshl_add_u64 v[108:109], v[108:109], 0, v[162:163]
	v_pk_mul_f32 v[110:111], v[156:157], v[114:115] op_sel_hi:[0,1]
	v_pk_mul_f32 v[114:115], v[156:157], v[106:107] op_sel_hi:[0,1]
	v_pk_mul_f32 v[106:107], v[156:157], v[104:105] op_sel_hi:[0,1]
	v_cvt_pk_bf16_f32 v104, v112, v113
	v_cvt_pk_bf16_f32 v105, v110, v111
	v_cvt_pk_bf16_f32 v106, v106, v107
	v_cvt_pk_bf16_f32 v107, v114, v115
	global_store_dwordx4 v[108:109], v[104:107], off
	v_pk_mul_f32 v[102:103], v[156:157], v[102:103] op_sel_hi:[0,1]
	v_pk_mul_f32 v[96:97], v[154:155], v[96:97] op_sel_hi:[0,1]
	v_pk_mul_f32 v[104:105], v[156:157], v[94:95] op_sel_hi:[0,1]
	v_pk_mul_f32 v[94:95], v[156:157], v[92:93] op_sel_hi:[0,1]
	v_cvt_pk_bf16_f32 v92, v100, v101
	v_cvt_pk_bf16_f32 v93, v102, v103
	v_cvt_pk_bf16_f32 v94, v94, v95
	v_cvt_pk_bf16_f32 v95, v104, v105
	global_store_dwordx4 v[108:109], v[92:95], off offset:256
	v_pk_mul_f32 v[84:85], v[154:155], v[84:85] op_sel_hi:[0,1]
	v_pk_mul_f32 v[86:87], v[154:155], v[86:87] op_sel_hi:[0,1]
	v_or_b32_e32 v92, 32, v157
	v_mad_i64_i32 v[92:93], s[42:43], v92, s78, v[160:161]
	v_lshl_add_u64 v[92:93], v[92:93], 0, v[162:163]
	v_pk_mul_f32 v[94:95], v[154:155], v[98:99] op_sel_hi:[0,1]
	v_pk_mul_f32 v[98:99], v[154:155], v[90:91] op_sel_hi:[0,1]
	v_pk_mul_f32 v[90:91], v[154:155], v[88:89] op_sel_hi:[0,1]
	v_cvt_pk_bf16_f32 v88, v96, v97
	v_cvt_pk_bf16_f32 v89, v94, v95
	v_cvt_pk_bf16_f32 v90, v90, v91
	v_cvt_pk_bf16_f32 v91, v98, v99
	global_store_dwordx4 v[92:93], v[88:91], off
	v_pk_mul_f32 v[80:81], v[152:153], v[80:81] op_sel_hi:[0,1]
	v_pk_mul_f32 v[68:69], v[152:153], v[68:69] op_sel_hi:[0,1]
	v_pk_mul_f32 v[88:89], v[154:155], v[78:79] op_sel_hi:[0,1]
	v_pk_mul_f32 v[78:79], v[154:155], v[76:77] op_sel_hi:[0,1]
	v_cvt_pk_bf16_f32 v76, v84, v85
	v_cvt_pk_bf16_f32 v77, v86, v87
	v_cvt_pk_bf16_f32 v78, v78, v79
	v_cvt_pk_bf16_f32 v79, v88, v89
	global_store_dwordx4 v[92:93], v[76:79], off offset:256
	v_pk_mul_f32 v[70:71], v[152:153], v[70:71] op_sel_hi:[0,1]
	v_pk_mul_f32 v[62:63], v[150:151], v[62:63] op_sel_hi:[0,1]
	v_or_b32_e32 v76, 48, v157
	v_mad_i64_i32 v[76:77], s[42:43], v76, s78, v[160:161]
	v_lshl_add_u64 v[76:77], v[76:77], 0, v[162:163]
	v_pk_mul_f32 v[78:79], v[152:153], v[82:83] op_sel_hi:[0,1]
	v_pk_mul_f32 v[82:83], v[152:153], v[74:75] op_sel_hi:[0,1]
	v_pk_mul_f32 v[74:75], v[152:153], v[72:73] op_sel_hi:[0,1]
	v_cvt_pk_bf16_f32 v72, v80, v81
	v_cvt_pk_bf16_f32 v73, v78, v79
	v_cvt_pk_bf16_f32 v74, v74, v75
	v_cvt_pk_bf16_f32 v75, v82, v83
	global_store_dwordx4 v[76:77], v[72:75], off
	v_pk_mul_f32 v[60:61], v[150:151], v[60:61] op_sel_hi:[0,1]
	v_pk_mul_f32 v[52:53], v[150:151], v[52:53] op_sel_hi:[0,1]
	v_pk_mul_f32 v[72:73], v[152:153], v[66:67] op_sel_hi:[0,1]
	v_pk_mul_f32 v[66:67], v[152:153], v[64:65] op_sel_hi:[0,1]
	v_cvt_pk_bf16_f32 v64, v68, v69
	v_cvt_pk_bf16_f32 v65, v70, v71
	v_cvt_pk_bf16_f32 v66, v66, v67
	v_cvt_pk_bf16_f32 v67, v72, v73
	global_store_dwordx4 v[76:77], v[64:67], off offset:256
	v_pk_mul_f32 v[54:55], v[150:151], v[54:55] op_sel_hi:[0,1]
	v_pk_mul_f32 v[48:49], v[140:141], v[48:49] op_sel_hi:[0,1]
	v_add_u32_e32 v64, 0x80, v157
	v_mad_i64_i32 v[64:65], s[42:43], v64, s78, v[160:161]
	v_lshl_add_u64 v[64:65], v[64:65], 0, v[162:163]
	v_pk_mul_f32 v[66:67], v[150:151], v[58:59] op_sel_hi:[0,1]
	v_pk_mul_f32 v[58:59], v[150:151], v[56:57] op_sel_hi:[0,1]
	v_cvt_pk_bf16_f32 v56, v60, v61
	v_cvt_pk_bf16_f32 v57, v62, v63
	v_cvt_pk_bf16_f32 v58, v58, v59
	v_cvt_pk_bf16_f32 v59, v66, v67
	global_store_dwordx4 v[64:65], v[56:59], off
	v_pk_mul_f32 v[36:37], v[140:141], v[36:37] op_sel_hi:[0,1]
	v_pk_mul_f32 v[38:39], v[140:141], v[38:39] op_sel_hi:[0,1]
	v_pk_mul_f32 v[56:57], v[150:151], v[46:47] op_sel_hi:[0,1]
	v_pk_mul_f32 v[46:47], v[150:151], v[44:45] op_sel_hi:[0,1]
	v_cvt_pk_bf16_f32 v44, v52, v53
	v_cvt_pk_bf16_f32 v45, v54, v55
	v_cvt_pk_bf16_f32 v46, v46, v47
	v_cvt_pk_bf16_f32 v47, v56, v57
	global_store_dwordx4 v[64:65], v[44:47], off offset:256
	v_pk_mul_f32 v[32:33], v[138:139], v[32:33] op_sel_hi:[0,1]
	v_pk_mul_f32 v[20:21], v[138:139], v[20:21] op_sel_hi:[0,1]
	v_add_u32_e32 v44, 0x90, v157
	v_mad_i64_i32 v[44:45], s[42:43], v44, s78, v[160:161]
	v_lshl_add_u64 v[44:45], v[44:45], 0, v[162:163]
	v_pk_mul_f32 v[46:47], v[140:141], v[50:51] op_sel_hi:[0,1]
	v_pk_mul_f32 v[50:51], v[140:141], v[42:43] op_sel_hi:[0,1]
	v_pk_mul_f32 v[42:43], v[140:141], v[40:41] op_sel_hi:[0,1]
	v_cvt_pk_bf16_f32 v40, v48, v49
	v_cvt_pk_bf16_f32 v41, v46, v47
	v_cvt_pk_bf16_f32 v42, v42, v43
	v_cvt_pk_bf16_f32 v43, v50, v51
	global_store_dwordx4 v[44:45], v[40:43], off
	v_pk_mul_f32 v[22:23], v[138:139], v[22:23] op_sel_hi:[0,1]
	v_pk_mul_f32 v[16:17], v[136:137], v[16:17] op_sel_hi:[0,1]
	v_pk_mul_f32 v[40:41], v[140:141], v[30:31] op_sel_hi:[0,1]
	v_pk_mul_f32 v[30:31], v[140:141], v[28:29] op_sel_hi:[0,1]
	v_cvt_pk_bf16_f32 v28, v36, v37
	v_cvt_pk_bf16_f32 v29, v38, v39
	v_cvt_pk_bf16_f32 v30, v30, v31
	v_cvt_pk_bf16_f32 v31, v40, v41
	global_store_dwordx4 v[44:45], v[28:31], off offset:256
	s_and_b64 vcc, s[8:9], exec
	v_pk_mul_f32 v[6:7], v[136:137], v[6:7] op_sel_hi:[0,1]
	v_add_u32_e32 v28, 0xa0, v157
	v_mad_i64_i32 v[28:29], s[42:43], v28, s78, v[160:161]
	v_lshl_add_u64 v[28:29], v[28:29], 0, v[162:163]
	v_pk_mul_f32 v[30:31], v[138:139], v[34:35] op_sel_hi:[0,1]
	v_pk_mul_f32 v[34:35], v[138:139], v[26:27] op_sel_hi:[0,1]
	v_pk_mul_f32 v[26:27], v[138:139], v[24:25] op_sel_hi:[0,1]
	v_cvt_pk_bf16_f32 v24, v32, v33
	v_cvt_pk_bf16_f32 v25, v30, v31
	v_cvt_pk_bf16_f32 v26, v26, v27
	v_cvt_pk_bf16_f32 v27, v34, v35
	global_store_dwordx4 v[28:29], v[24:27], off
	v_pk_mul_f32 v[4:5], v[136:137], v[4:5] op_sel_hi:[0,1]
	s_nop 0
	v_pk_mul_f32 v[24:25], v[138:139], v[14:15] op_sel_hi:[0,1]
	v_pk_mul_f32 v[14:15], v[138:139], v[12:13] op_sel_hi:[0,1]
	v_cvt_pk_bf16_f32 v12, v20, v21
	v_cvt_pk_bf16_f32 v13, v22, v23
	v_cvt_pk_bf16_f32 v14, v14, v15
	v_cvt_pk_bf16_f32 v15, v24, v25
	global_store_dwordx4 v[28:29], v[12:15], off offset:256
	s_nop 1
	v_add_u32_e32 v12, 0xb0, v157
	v_mad_i64_i32 v[12:13], s[42:43], v12, s78, v[160:161]
	v_lshl_add_u64 v[12:13], v[12:13], 0, v[162:163]
	v_pk_mul_f32 v[14:15], v[136:137], v[18:19] op_sel_hi:[0,1]
	v_pk_mul_f32 v[18:19], v[136:137], v[10:11] op_sel_hi:[0,1]
	v_pk_mul_f32 v[10:11], v[136:137], v[8:9] op_sel_hi:[0,1]
	v_cvt_pk_bf16_f32 v8, v16, v17
	v_cvt_pk_bf16_f32 v9, v14, v15
	v_cvt_pk_bf16_f32 v10, v10, v11
	v_cvt_pk_bf16_f32 v11, v18, v19
	global_store_dwordx4 v[12:13], v[8:11], off
	s_mov_b64 s[42:43], -1
	s_nop 0
	v_pk_mul_f32 v[8:9], v[136:137], v[2:3] op_sel_hi:[0,1]
	v_pk_mul_f32 v[2:3], v[136:137], v[0:1] op_sel_hi:[0,1]
	v_cvt_pk_bf16_f32 v0, v4, v5
	v_cvt_pk_bf16_f32 v1, v6, v7
	v_cvt_pk_bf16_f32 v2, v2, v3
	v_cvt_pk_bf16_f32 v3, v8, v9
	global_store_dwordx4 v[12:13], v[0:3], off offset:256
	s_cbranch_vccz .LBB0_295
	s_nop 0
	v_lshl_add_u32 v0, s79, 8, v137
	v_ashrrev_i32_e32 v1, 31, v0
	v_lshl_add_u64 v[0:1], v[0:1], 2, s[72:73]
	global_load_dword v158, v[0:1], off
	global_load_dword v156, v[0:1], off offset:64
	global_load_dword v154, v[0:1], off offset:128
	global_load_dword v152, v[0:1], off offset:192
	global_load_dword v150, v[0:1], off offset:512
	global_load_dword v140, v[0:1], off offset:576
	global_load_dword v138, v[0:1], off offset:640
	global_load_dword v136, v[0:1], off offset:704
	s_mov_b64 s[42:43], 0
	s_branch .LBB0_295

.LBB0_325:
	ds_read_b128 v[160:163], v151
	ds_read_b128 v[164:167], v151 offset:1024
	ds_read_b128 v[168:171], v151 offset:2048
	ds_read_b128 v[176:179], v151 offset:3072
	s_add_u32 s48, s46, 0x100
	s_addc_u32 s49, s47, 0
	s_cmp_eq_u32 s91, 4
	s_cselect_b32 s53, s43, s49
	s_cselect_b32 s52, s42, s48
	s_cselect_b32 s51, s41, s90
	s_cselect_b32 s50, s62, s63
	v_lshl_add_u64 v[214:215], s[46:47], 0, v[142:143]
	s_add_i32 m0, s55, 0xc000
	ds_read_b128 v[180:183], v153
	ds_read_b128 v[186:189], v153 offset:1024
	ds_read_b128 v[190:193], v153 offset:2048
	ds_read_b128 v[194:197], v153 offset:3072
	ds_read_b128 v[198:201], v153 offset:4096
	ds_read_b128 v[202:205], v153 offset:5120
	ds_read_b128 v[206:209], v153 offset:6144
	ds_read_b128 v[210:213], v153 offset:7168
	global_load_lds_dwordx4 v[214:215], off
	s_add_i32 m0, s55, 0xe000
	v_lshl_add_u64 v[214:215], s[46:47], 0, v[144:145]
	global_load_lds_dwordx4 v[214:215], off
	s_waitcnt lgkmcnt(8)
	s_barrier
	s_waitcnt lgkmcnt(0)
	v_mfma_f32_16x16x32_bf16 v[124:127], v[160:163], v[180:183], v[124:127]
	v_mfma_f32_16x16x32_bf16 v[124:127], v[164:167], v[186:189], v[124:127]
	v_mfma_f32_16x16x32_bf16 v[120:123], v[168:171], v[180:183], v[120:123]
	v_mfma_f32_16x16x32_bf16 v[120:123], v[176:179], v[186:189], v[120:123]
	v_mfma_f32_16x16x32_bf16 v[108:111], v[160:163], v[190:193], v[108:111]
	v_mfma_f32_16x16x32_bf16 v[108:111], v[164:167], v[194:197], v[108:111]
	v_mfma_f32_16x16x32_bf16 v[104:107], v[168:171], v[190:193], v[104:107]
	v_mfma_f32_16x16x32_bf16 v[104:107], v[176:179], v[194:197], v[104:107]
	v_mfma_f32_16x16x32_bf16 v[92:95], v[160:163], v[198:201], v[92:95]
	v_mfma_f32_16x16x32_bf16 v[92:95], v[164:167], v[202:205], v[92:95]
	v_mfma_f32_16x16x32_bf16 v[88:91], v[168:171], v[198:201], v[88:91]
	v_mfma_f32_16x16x32_bf16 v[88:91], v[176:179], v[202:205], v[88:91]
	v_mfma_f32_16x16x32_bf16 v[76:79], v[160:163], v[206:209], v[76:79]
	v_mfma_f32_16x16x32_bf16 v[76:79], v[164:167], v[210:213], v[76:79]
	v_mfma_f32_16x16x32_bf16 v[72:75], v[168:171], v[206:209], v[72:75]
	v_mfma_f32_16x16x32_bf16 v[72:75], v[176:179], v[210:213], v[72:75]
	s_barrier
	s_add_i32 s46, s81, s54
	v_lshl_add_u64 v[230:231], s[50:51], 0, v[130:131]
	s_mov_b32 m0, s46
	ds_read_b128 v[214:217], v155
	ds_read_b128 v[218:221], v155 offset:1024
	ds_read_b128 v[222:225], v155 offset:2048
	ds_read_b128 v[226:229], v155 offset:3072
	global_load_lds_dwordx4 v[230:231], off
	s_add_i32 m0, s46, 0x2000
	v_lshl_add_u64 v[232:233], s[50:51], 0, v[134:135]
	global_load_lds_dwordx4 v[232:233], off
	s_barrier
	s_waitcnt lgkmcnt(0)
	v_mfma_f32_16x16x32_bf16 v[116:119], v[214:217], v[180:183], v[116:119]
	v_mfma_f32_16x16x32_bf16 v[116:119], v[218:221], v[186:189], v[116:119]
	v_mfma_f32_16x16x32_bf16 v[112:115], v[222:225], v[180:183], v[112:115]
	v_mfma_f32_16x16x32_bf16 v[112:115], v[226:229], v[186:189], v[112:115]
	v_mfma_f32_16x16x32_bf16 v[100:103], v[214:217], v[190:193], v[100:103]
	v_mfma_f32_16x16x32_bf16 v[100:103], v[218:221], v[194:197], v[100:103]
	v_mfma_f32_16x16x32_bf16 v[96:99], v[222:225], v[190:193], v[96:99]
	v_mfma_f32_16x16x32_bf16 v[96:99], v[226:229], v[194:197], v[96:99]
	v_mfma_f32_16x16x32_bf16 v[84:87], v[214:217], v[198:201], v[84:87]
	v_mfma_f32_16x16x32_bf16 v[84:87], v[218:221], v[202:205], v[84:87]
	v_mfma_f32_16x16x32_bf16 v[80:83], v[222:225], v[198:201], v[80:83]
	v_mfma_f32_16x16x32_bf16 v[80:83], v[226:229], v[202:205], v[80:83]
	v_mfma_f32_16x16x32_bf16 v[68:71], v[214:217], v[206:209], v[68:71]
	v_mfma_f32_16x16x32_bf16 v[68:71], v[218:221], v[210:213], v[68:71]
	v_mfma_f32_16x16x32_bf16 v[64:67], v[222:225], v[206:209], v[64:67]
	v_mfma_f32_16x16x32_bf16 v[64:67], v[226:229], v[210:213], v[64:67]
	s_mov_b32 m0, s55
	v_lshl_add_u64 v[234:235], s[52:53], 0, v[128:129]
	s_barrier
	ds_read_b128 v[180:183], v153 offset:16384
	ds_read_b128 v[186:189], v153 offset:17408
	ds_read_b128 v[190:193], v153 offset:18432
	ds_read_b128 v[194:197], v153 offset:19456
	ds_read_b128 v[198:201], v153 offset:20480
	ds_read_b128 v[202:205], v153 offset:21504
	ds_read_b128 v[206:209], v153 offset:22528
	ds_read_b128 v[210:213], v153 offset:23552
	global_load_lds_dwordx4 v[234:235], off
	s_mov_b32 m0, s61
	v_lshl_add_u64 v[236:237], s[52:53], 0, v[132:133]
	global_load_lds_dwordx4 v[236:237], off
	s_barrier
	s_waitcnt lgkmcnt(0)
	v_mfma_f32_16x16x32_bf16 v[60:63], v[160:163], v[180:183], v[60:63]
	v_mfma_f32_16x16x32_bf16 v[60:63], v[164:167], v[186:189], v[60:63]
	v_mfma_f32_16x16x32_bf16 v[56:59], v[168:171], v[180:183], v[56:59]
	v_mfma_f32_16x16x32_bf16 v[56:59], v[176:179], v[186:189], v[56:59]
	v_mfma_f32_16x16x32_bf16 v[48:51], v[160:163], v[190:193], v[48:51]
	v_mfma_f32_16x16x32_bf16 v[48:51], v[164:167], v[194:197], v[48:51]
	v_mfma_f32_16x16x32_bf16 v[40:43], v[168:171], v[190:193], v[40:43]
	v_mfma_f32_16x16x32_bf16 v[40:43], v[176:179], v[194:197], v[40:43]
	v_mfma_f32_16x16x32_bf16 v[32:35], v[160:163], v[198:201], v[32:35]
	v_mfma_f32_16x16x32_bf16 v[32:35], v[164:167], v[202:205], v[32:35]
	v_mfma_f32_16x16x32_bf16 v[24:27], v[168:171], v[198:201], v[24:27]
	v_mfma_f32_16x16x32_bf16 v[24:27], v[176:179], v[202:205], v[24:27]
	v_mfma_f32_16x16x32_bf16 v[16:19], v[160:163], v[206:209], v[16:19]
	v_mfma_f32_16x16x32_bf16 v[16:19], v[164:167], v[210:213], v[16:19]
	v_mfma_f32_16x16x32_bf16 v[8:11], v[168:171], v[206:209], v[8:11]
	v_mfma_f32_16x16x32_bf16 v[8:11], v[176:179], v[210:213], v[8:11]
	s_barrier
	s_add_u32 s46, s50, 0x20000
	s_addc_u32 s47, s51, 0
	s_add_i32 s92, s82, s54
	s_mov_b32 m0, s92
	v_lshl_add_u64 v[160:161], s[46:47], 0, v[130:131]
	global_load_lds_dwordx4 v[160:161], off
	s_add_i32 m0, s92, 0x2000
	v_lshl_add_u64 v[160:161], s[46:47], 0, v[134:135]
	global_load_lds_dwordx4 v[160:161], off
	s_waitcnt vmcnt(6)
	s_barrier
	v_mfma_f32_16x16x32_bf16 v[52:55], v[214:217], v[180:183], v[52:55]
	v_mfma_f32_16x16x32_bf16 v[52:55], v[218:221], v[186:189], v[52:55]
	v_mfma_f32_16x16x32_bf16 v[44:47], v[222:225], v[180:183], v[44:47]
	v_mfma_f32_16x16x32_bf16 v[44:47], v[226:229], v[186:189], v[44:47]
	v_mfma_f32_16x16x32_bf16 v[36:39], v[214:217], v[190:193], v[36:39]
	v_mfma_f32_16x16x32_bf16 v[36:39], v[218:221], v[194:197], v[36:39]
	v_mfma_f32_16x16x32_bf16 v[28:31], v[222:225], v[190:193], v[28:31]
	v_mfma_f32_16x16x32_bf16 v[28:31], v[226:229], v[194:197], v[28:31]
	v_mfma_f32_16x16x32_bf16 v[20:23], v[214:217], v[198:201], v[20:23]
	v_mfma_f32_16x16x32_bf16 v[20:23], v[218:221], v[202:205], v[20:23]
	v_mfma_f32_16x16x32_bf16 v[12:15], v[222:225], v[198:201], v[12:15]
	v_mfma_f32_16x16x32_bf16 v[12:15], v[226:229], v[202:205], v[12:15]
	v_mfma_f32_16x16x32_bf16 v[4:7], v[214:217], v[206:209], v[4:7]
	v_mfma_f32_16x16x32_bf16 v[4:7], v[218:221], v[210:213], v[4:7]
	v_mfma_f32_16x16x32_bf16 v[0:3], v[222:225], v[206:209], v[0:3]
	v_mfma_f32_16x16x32_bf16 v[0:3], v[226:229], v[210:213], v[0:3]
	s_add_i32 s92, 0, 0x18000
	v_add_u32_e32 v157, s92, v139
	s_barrier
	ds_read_b128 v[160:163], v157
	ds_read_b128 v[164:167], v157 offset:1024
	ds_read_b128 v[168:171], v157 offset:2048
	ds_read_b128 v[176:179], v157 offset:3072
	s_add_u32 s46, s52, 0x170000
	s_addc_u32 s47, s53, 0
	s_mov_b32 m0, s74
	v_lshl_add_u64 v[214:215], s[46:47], 0, v[128:129]
	ds_read_b128 v[180:183], v153 offset:32768
	ds_read_b128 v[186:189], v153 offset:33792
	ds_read_b128 v[190:193], v153 offset:34816
	ds_read_b128 v[194:197], v153 offset:35840
	ds_read_b128 v[198:201], v153 offset:36864
	ds_read_b128 v[202:205], v153 offset:37888
	ds_read_b128 v[206:209], v153 offset:38912
	ds_read_b128 v[210:213], v153 offset:39936
	global_load_lds_dwordx4 v[214:215], off
	s_mov_b32 m0, s75
	v_lshl_add_u64 v[214:215], s[46:47], 0, v[132:133]
	global_load_lds_dwordx4 v[214:215], off
	s_waitcnt lgkmcnt(8)
	s_barrier
	s_waitcnt lgkmcnt(0)
	v_mfma_f32_16x16x32_bf16 v[124:127], v[160:163], v[180:183], v[124:127]
	v_mfma_f32_16x16x32_bf16 v[124:127], v[164:167], v[186:189], v[124:127]
	v_mfma_f32_16x16x32_bf16 v[120:123], v[168:171], v[180:183], v[120:123]
	v_mfma_f32_16x16x32_bf16 v[120:123], v[176:179], v[186:189], v[120:123]
	v_mfma_f32_16x16x32_bf16 v[108:111], v[160:163], v[190:193], v[108:111]
	v_mfma_f32_16x16x32_bf16 v[108:111], v[164:167], v[194:197], v[108:111]
	v_mfma_f32_16x16x32_bf16 v[104:107], v[168:171], v[190:193], v[104:107]
	v_mfma_f32_16x16x32_bf16 v[104:107], v[176:179], v[194:197], v[104:107]
	v_mfma_f32_16x16x32_bf16 v[92:95], v[160:163], v[198:201], v[92:95]
	v_mfma_f32_16x16x32_bf16 v[92:95], v[164:167], v[202:205], v[92:95]
	v_mfma_f32_16x16x32_bf16 v[88:91], v[168:171], v[198:201], v[88:91]
	v_mfma_f32_16x16x32_bf16 v[88:91], v[176:179], v[202:205], v[88:91]
	v_mfma_f32_16x16x32_bf16 v[76:79], v[160:163], v[206:209], v[76:79]
	v_mfma_f32_16x16x32_bf16 v[76:79], v[164:167], v[210:213], v[76:79]
	v_mfma_f32_16x16x32_bf16 v[72:75], v[168:171], v[206:209], v[72:75]
	v_mfma_f32_16x16x32_bf16 v[72:75], v[176:179], v[210:213], v[72:75]
	s_barrier
	s_add_i32 s52, 0, 0x1c000
	s_add_i32 s46, s92, s54
	v_add_u32_e32 v157, s52, v139
	v_lshl_add_u64 v[230:231], v[230:231], 0, s[10:11]
	s_mov_b32 m0, s46
	ds_read_b128 v[214:217], v157
	ds_read_b128 v[218:221], v157 offset:1024
	ds_read_b128 v[222:225], v157 offset:2048
	ds_read_b128 v[226:229], v157 offset:3072
	global_load_lds_dwordx4 v[230:231], off
	s_add_i32 m0, s46, 0x2000
	v_lshl_add_u64 v[230:231], v[232:233], 0, s[10:11]
	global_load_lds_dwordx4 v[230:231], off
	s_barrier
	s_waitcnt lgkmcnt(0)
	v_mfma_f32_16x16x32_bf16 v[116:119], v[214:217], v[180:183], v[116:119]
	v_mfma_f32_16x16x32_bf16 v[116:119], v[218:221], v[186:189], v[116:119]
	v_mfma_f32_16x16x32_bf16 v[112:115], v[222:225], v[180:183], v[112:115]
	v_mfma_f32_16x16x32_bf16 v[112:115], v[226:229], v[186:189], v[112:115]
	v_mfma_f32_16x16x32_bf16 v[100:103], v[214:217], v[190:193], v[100:103]
	v_mfma_f32_16x16x32_bf16 v[100:103], v[218:221], v[194:197], v[100:103]
	v_mfma_f32_16x16x32_bf16 v[96:99], v[222:225], v[190:193], v[96:99]
	v_mfma_f32_16x16x32_bf16 v[96:99], v[226:229], v[194:197], v[96:99]
	v_mfma_f32_16x16x32_bf16 v[84:87], v[214:217], v[198:201], v[84:87]
	v_mfma_f32_16x16x32_bf16 v[84:87], v[218:221], v[202:205], v[84:87]
	v_mfma_f32_16x16x32_bf16 v[80:83], v[222:225], v[198:201], v[80:83]
	v_mfma_f32_16x16x32_bf16 v[80:83], v[226:229], v[202:205], v[80:83]
	v_mfma_f32_16x16x32_bf16 v[68:71], v[214:217], v[206:209], v[68:71]
	v_mfma_f32_16x16x32_bf16 v[68:71], v[218:221], v[210:213], v[68:71]
	v_mfma_f32_16x16x32_bf16 v[64:67], v[222:225], v[206:209], v[64:67]
	v_mfma_f32_16x16x32_bf16 v[64:67], v[226:229], v[210:213], v[64:67]
	s_mov_b32 m0, s77
	v_lshl_add_u64 v[230:231], v[234:235], 0, s[10:11]
	s_barrier
	ds_read_b128 v[180:183], v153 offset:49152
	ds_read_b128 v[186:189], v153 offset:50176
	ds_read_b128 v[190:193], v153 offset:51200
	ds_read_b128 v[194:197], v153 offset:52224
	ds_read_b128 v[198:201], v153 offset:53248
	ds_read_b128 v[202:205], v153 offset:54272
	ds_read_b128 v[206:209], v153 offset:55296
	ds_read_b128 v[210:213], v153 offset:56320
	global_load_lds_dwordx4 v[230:231], off
	s_mov_b32 m0, s78
	v_lshl_add_u64 v[230:231], v[236:237], 0, s[10:11]
	global_load_lds_dwordx4 v[230:231], off
	s_barrier
	s_waitcnt lgkmcnt(0)
	v_mfma_f32_16x16x32_bf16 v[60:63], v[160:163], v[180:183], v[60:63]
	v_mfma_f32_16x16x32_bf16 v[60:63], v[164:167], v[186:189], v[60:63]
	v_mfma_f32_16x16x32_bf16 v[56:59], v[168:171], v[180:183], v[56:59]
	v_mfma_f32_16x16x32_bf16 v[56:59], v[176:179], v[186:189], v[56:59]
	v_mfma_f32_16x16x32_bf16 v[48:51], v[160:163], v[190:193], v[48:51]
	v_mfma_f32_16x16x32_bf16 v[48:51], v[164:167], v[194:197], v[48:51]
	v_mfma_f32_16x16x32_bf16 v[40:43], v[168:171], v[190:193], v[40:43]
	v_mfma_f32_16x16x32_bf16 v[40:43], v[176:179], v[194:197], v[40:43]
	v_mfma_f32_16x16x32_bf16 v[32:35], v[160:163], v[198:201], v[32:35]
	v_mfma_f32_16x16x32_bf16 v[32:35], v[164:167], v[202:205], v[32:35]
	v_mfma_f32_16x16x32_bf16 v[24:27], v[168:171], v[198:201], v[24:27]
	v_mfma_f32_16x16x32_bf16 v[24:27], v[176:179], v[202:205], v[24:27]
	v_mfma_f32_16x16x32_bf16 v[16:19], v[160:163], v[206:209], v[16:19]
	v_mfma_f32_16x16x32_bf16 v[16:19], v[164:167], v[210:213], v[16:19]
	v_mfma_f32_16x16x32_bf16 v[8:11], v[168:171], v[206:209], v[8:11]
	v_mfma_f32_16x16x32_bf16 v[8:11], v[176:179], v[210:213], v[8:11]
	s_barrier
	s_add_u32 s46, s50, 0x20080
	s_addc_u32 s47, s51, 0
	s_add_i32 s50, s52, s54
	s_mov_b32 m0, s50
	v_lshl_add_u64 v[160:161], s[46:47], 0, v[130:131]
	global_load_lds_dwordx4 v[160:161], off
	s_add_i32 m0, s50, 0x2000
	v_lshl_add_u64 v[160:161], s[46:47], 0, v[134:135]
	global_load_lds_dwordx4 v[160:161], off
	s_waitcnt vmcnt(6)
	s_barrier
	v_mfma_f32_16x16x32_bf16 v[52:55], v[214:217], v[180:183], v[52:55]
	v_mfma_f32_16x16x32_bf16 v[52:55], v[218:221], v[186:189], v[52:55]
	v_mfma_f32_16x16x32_bf16 v[44:47], v[222:225], v[180:183], v[44:47]
	v_mfma_f32_16x16x32_bf16 v[44:47], v[226:229], v[186:189], v[44:47]
	v_mfma_f32_16x16x32_bf16 v[36:39], v[214:217], v[190:193], v[36:39]
	v_mfma_f32_16x16x32_bf16 v[36:39], v[218:221], v[194:197], v[36:39]
	v_mfma_f32_16x16x32_bf16 v[28:31], v[222:225], v[190:193], v[28:31]
	v_mfma_f32_16x16x32_bf16 v[28:31], v[226:229], v[194:197], v[28:31]
	v_mfma_f32_16x16x32_bf16 v[20:23], v[214:217], v[198:201], v[20:23]
	v_mfma_f32_16x16x32_bf16 v[20:23], v[218:221], v[202:205], v[20:23]
	v_mfma_f32_16x16x32_bf16 v[12:15], v[222:225], v[198:201], v[12:15]
	v_mfma_f32_16x16x32_bf16 v[12:15], v[226:229], v[202:205], v[12:15]
	v_mfma_f32_16x16x32_bf16 v[4:7], v[214:217], v[206:209], v[4:7]
	v_mfma_f32_16x16x32_bf16 v[4:7], v[218:221], v[210:213], v[4:7]
	v_mfma_f32_16x16x32_bf16 v[0:3], v[222:225], v[206:209], v[0:3]
	v_mfma_f32_16x16x32_bf16 v[0:3], v[226:229], v[210:213], v[0:3]
	s_add_i32 s91, s91, 2
	s_add_u32 s63, s63, 0x100
	s_addc_u32 s90, s90, 0
	s_cmp_gt_u32 s91, 5
	s_mov_b64 s[46:47], s[48:49]
	s_barrier
	s_cbranch_scc0 .LBB0_325
	v_lshl_add_u32 v162, s88, 8, v137
	v_lshl_or_b32 v160, s89, 8, v141
	v_ashrrev_i32_e32 v163, 31, v162
	v_ashrrev_i32_e32 v161, 31, v160
	v_lshlrev_b64 v[164:165], 14, v[162:163]
	v_lshl_add_u64 v[164:165], s[56:57], 0, v[164:165]
	v_lshlrev_b64 v[166:167], 1, v[160:161]
	v_lshl_add_u64 v[160:161], v[164:165], 0, v[166:167]
	s_waitcnt vmcnt(0)
	v_pk_mul_f32 v[126:127], v[158:159], v[126:127] op_sel_hi:[0,1]
	v_pk_mul_f32 v[124:125], v[158:159], v[124:125] op_sel_hi:[0,1]
	v_pk_mul_f32 v[164:165], v[158:159], v[122:123] op_sel_hi:[0,1]
	v_pk_mul_f32 v[122:123], v[158:159], v[120:121] op_sel_hi:[0,1]
	v_cvt_pk_bf16_f32 v120, v124, v125
	v_cvt_pk_bf16_f32 v121, v126, v127
	v_cvt_pk_bf16_f32 v122, v122, v123
	v_cvt_pk_bf16_f32 v123, v164, v165
	global_store_dwordx4 v[160:161], v[120:123], off
	v_pk_mul_f32 v[116:117], v[158:159], v[116:117] op_sel_hi:[0,1]
	v_pk_mul_f32 v[118:119], v[158:159], v[118:119] op_sel_hi:[0,1]
	v_pk_mul_f32 v[120:121], v[158:159], v[114:115] op_sel_hi:[0,1]
	v_pk_mul_f32 v[114:115], v[158:159], v[112:113] op_sel_hi:[0,1]
	v_cvt_pk_bf16_f32 v112, v116, v117
	v_cvt_pk_bf16_f32 v113, v118, v119
	v_cvt_pk_bf16_f32 v114, v114, v115
	v_cvt_pk_bf16_f32 v115, v120, v121
	global_store_dwordx4 v[160:161], v[112:115], off offset:256
	v_pk_mul_f32 v[110:111], v[156:157], v[110:111] op_sel_hi:[0,1]
	v_pk_mul_f32 v[108:109], v[156:157], v[108:109] op_sel_hi:[0,1]
	v_or_b32_e32 v112, 16, v162
	v_ashrrev_i32_e32 v113, 31, v112
	v_lshlrev_b64 v[112:113], 14, v[112:113]
	v_lshl_add_u64 v[112:113], s[56:57], 0, v[112:113]
	v_lshl_add_u64 v[112:113], v[112:113], 0, v[166:167]
	v_pk_mul_f32 v[114:115], v[156:157], v[106:107] op_sel_hi:[0,1]
	v_pk_mul_f32 v[106:107], v[156:157], v[104:105] op_sel_hi:[0,1]
	v_cvt_pk_bf16_f32 v104, v108, v109
	v_cvt_pk_bf16_f32 v105, v110, v111
	v_cvt_pk_bf16_f32 v106, v106, v107
	v_cvt_pk_bf16_f32 v107, v114, v115
	global_store_dwordx4 v[112:113], v[104:107], off
	v_pk_mul_f32 v[100:101], v[156:157], v[100:101] op_sel_hi:[0,1]
	v_pk_mul_f32 v[102:103], v[156:157], v[102:103] op_sel_hi:[0,1]
	v_pk_mul_f32 v[104:105], v[156:157], v[98:99] op_sel_hi:[0,1]
	v_pk_mul_f32 v[98:99], v[156:157], v[96:97] op_sel_hi:[0,1]
	v_cvt_pk_bf16_f32 v96, v100, v101
	v_cvt_pk_bf16_f32 v97, v102, v103
	v_cvt_pk_bf16_f32 v98, v98, v99
	v_cvt_pk_bf16_f32 v99, v104, v105
	global_store_dwordx4 v[112:113], v[96:99], off offset:256
	v_pk_mul_f32 v[94:95], v[154:155], v[94:95] op_sel_hi:[0,1]
	v_pk_mul_f32 v[92:93], v[154:155], v[92:93] op_sel_hi:[0,1]
	v_or_b32_e32 v96, 32, v162
	v_ashrrev_i32_e32 v97, 31, v96
	v_lshlrev_b64 v[96:97], 14, v[96:97]
	v_lshl_add_u64 v[96:97], s[56:57], 0, v[96:97]
	v_lshl_add_u64 v[96:97], v[96:97], 0, v[166:167]
	v_pk_mul_f32 v[98:99], v[154:155], v[90:91] op_sel_hi:[0,1]
	v_pk_mul_f32 v[90:91], v[154:155], v[88:89] op_sel_hi:[0,1]
	v_cvt_pk_bf16_f32 v88, v92, v93
	v_cvt_pk_bf16_f32 v89, v94, v95
	v_cvt_pk_bf16_f32 v90, v90, v91
	v_cvt_pk_bf16_f32 v91, v98, v99
	global_store_dwordx4 v[96:97], v[88:91], off
	v_pk_mul_f32 v[84:85], v[154:155], v[84:85] op_sel_hi:[0,1]
	v_pk_mul_f32 v[86:87], v[154:155], v[86:87] op_sel_hi:[0,1]
	v_pk_mul_f32 v[88:89], v[154:155], v[82:83] op_sel_hi:[0,1]
	v_pk_mul_f32 v[82:83], v[154:155], v[80:81] op_sel_hi:[0,1]
	v_cvt_pk_bf16_f32 v80, v84, v85
	v_cvt_pk_bf16_f32 v81, v86, v87
	v_cvt_pk_bf16_f32 v82, v82, v83
	v_cvt_pk_bf16_f32 v83, v88, v89
	global_store_dwordx4 v[96:97], v[80:83], off offset:256
	v_pk_mul_f32 v[78:79], v[152:153], v[78:79] op_sel_hi:[0,1]
	v_pk_mul_f32 v[76:77], v[152:153], v[76:77] op_sel_hi:[0,1]
	v_or_b32_e32 v80, 48, v162
	v_ashrrev_i32_e32 v81, 31, v80
	v_lshlrev_b64 v[80:81], 14, v[80:81]
	v_lshl_add_u64 v[80:81], s[56:57], 0, v[80:81]
	v_lshl_add_u64 v[80:81], v[80:81], 0, v[166:167]
	v_pk_mul_f32 v[82:83], v[152:153], v[74:75] op_sel_hi:[0,1]
	v_pk_mul_f32 v[74:75], v[152:153], v[72:73] op_sel_hi:[0,1]
	v_cvt_pk_bf16_f32 v72, v76, v77
	v_cvt_pk_bf16_f32 v73, v78, v79
	v_cvt_pk_bf16_f32 v74, v74, v75
	v_cvt_pk_bf16_f32 v75, v82, v83
	global_store_dwordx4 v[80:81], v[72:75], off
	v_pk_mul_f32 v[70:71], v[152:153], v[70:71] op_sel_hi:[0,1]
	v_pk_mul_f32 v[68:69], v[152:153], v[68:69] op_sel_hi:[0,1]
	v_pk_mul_f32 v[72:73], v[152:153], v[66:67] op_sel_hi:[0,1]
	v_pk_mul_f32 v[66:67], v[152:153], v[64:65] op_sel_hi:[0,1]
	v_cvt_pk_bf16_f32 v64, v68, v69
	v_cvt_pk_bf16_f32 v65, v70, v71
	v_cvt_pk_bf16_f32 v66, v66, v67
	v_cvt_pk_bf16_f32 v67, v72, v73
	v_pk_mul_f32 v[60:61], v[150:151], v[60:61] op_sel_hi:[0,1]
	global_store_dwordx4 v[80:81], v[64:67], off offset:256
	v_pk_mul_f32 v[62:63], v[150:151], v[62:63] op_sel_hi:[0,1]
	s_mov_b64 s[46:47], 0x200000
	v_pk_mul_f32 v[66:67], v[150:151], v[58:59] op_sel_hi:[0,1]
	v_pk_mul_f32 v[58:59], v[150:151], v[56:57] op_sel_hi:[0,1]
	v_cvt_pk_bf16_f32 v56, v60, v61
	v_add_co_u32_e32 v60, vcc, s83, v160
	v_cvt_pk_bf16_f32 v57, v62, v63
	v_cvt_pk_bf16_f32 v58, v58, v59
	v_cvt_pk_bf16_f32 v59, v66, v67
	v_lshl_add_u64 v[64:65], v[160:161], 0, s[46:47]
	s_nop 0
	v_addc_co_u32_e32 v61, vcc, 0, v161, vcc
	global_store_dwordx4 v[60:61], v[56:59], off
	v_pk_mul_f32 v[54:55], v[150:151], v[54:55] op_sel_hi:[0,1]
	v_pk_mul_f32 v[52:53], v[150:151], v[52:53] op_sel_hi:[0,1]
	v_pk_mul_f32 v[56:57], v[150:151], v[46:47] op_sel_hi:[0,1]
	v_pk_mul_f32 v[46:47], v[150:151], v[44:45] op_sel_hi:[0,1]
	v_cvt_pk_bf16_f32 v44, v52, v53
	v_cvt_pk_bf16_f32 v45, v54, v55
	v_cvt_pk_bf16_f32 v46, v46, v47
	v_cvt_pk_bf16_f32 v47, v56, v57
	global_store_dwordx4 v[64:65], v[44:47], off offset:256
	v_pk_mul_f32 v[48:49], v[140:141], v[48:49] op_sel_hi:[0,1]
	v_pk_mul_f32 v[38:39], v[140:141], v[38:39] op_sel_hi:[0,1]
	v_pk_mul_f32 v[46:47], v[140:141], v[50:51] op_sel_hi:[0,1]
	v_pk_mul_f32 v[50:51], v[140:141], v[42:43] op_sel_hi:[0,1]
	v_pk_mul_f32 v[42:43], v[140:141], v[40:41] op_sel_hi:[0,1]
	v_cvt_pk_bf16_f32 v40, v48, v49
	v_cvt_pk_bf16_f32 v41, v46, v47
	v_add_co_u32_e32 v46, vcc, s84, v160
	v_cvt_pk_bf16_f32 v42, v42, v43
	v_cvt_pk_bf16_f32 v43, v50, v51
	v_lshl_add_u64 v[44:45], v[160:161], 0, s[30:31]
	s_nop 0
	v_addc_co_u32_e32 v47, vcc, 0, v161, vcc
	global_store_dwordx4 v[46:47], v[40:43], off
	v_pk_mul_f32 v[36:37], v[140:141], v[36:37] op_sel_hi:[0,1]
	v_pk_mul_f32 v[32:33], v[138:139], v[32:33] op_sel_hi:[0,1]
	v_pk_mul_f32 v[40:41], v[140:141], v[30:31] op_sel_hi:[0,1]
	v_pk_mul_f32 v[30:31], v[140:141], v[28:29] op_sel_hi:[0,1]
	v_cvt_pk_bf16_f32 v28, v36, v37
	v_cvt_pk_bf16_f32 v29, v38, v39
	v_cvt_pk_bf16_f32 v30, v30, v31
	v_cvt_pk_bf16_f32 v31, v40, v41
	global_store_dwordx4 v[44:45], v[28:31], off offset:256
	v_pk_mul_f32 v[22:23], v[138:139], v[22:23] op_sel_hi:[0,1]
	v_pk_mul_f32 v[20:21], v[138:139], v[20:21] op_sel_hi:[0,1]
	v_pk_mul_f32 v[30:31], v[138:139], v[34:35] op_sel_hi:[0,1]
	v_pk_mul_f32 v[34:35], v[138:139], v[26:27] op_sel_hi:[0,1]
	v_pk_mul_f32 v[26:27], v[138:139], v[24:25] op_sel_hi:[0,1]
	v_cvt_pk_bf16_f32 v24, v32, v33
	v_cvt_pk_bf16_f32 v25, v30, v31
	v_add_co_u32_e32 v30, vcc, s85, v160
	v_cvt_pk_bf16_f32 v26, v26, v27
	v_cvt_pk_bf16_f32 v27, v34, v35
	v_lshl_add_u64 v[28:29], v[160:161], 0, s[36:37]
	s_nop 0
	v_addc_co_u32_e32 v31, vcc, 0, v161, vcc
	global_store_dwordx4 v[30:31], v[24:27], off
	v_pk_mul_f32 v[16:17], v[136:137], v[16:17] op_sel_hi:[0,1]
	s_mov_b64 s[46:47], -1
	v_pk_mul_f32 v[24:25], v[138:139], v[14:15] op_sel_hi:[0,1]
	v_pk_mul_f32 v[14:15], v[138:139], v[12:13] op_sel_hi:[0,1]
	v_cvt_pk_bf16_f32 v12, v20, v21
	v_cvt_pk_bf16_f32 v13, v22, v23
	v_cvt_pk_bf16_f32 v14, v14, v15
	v_cvt_pk_bf16_f32 v15, v24, v25
	global_store_dwordx4 v[28:29], v[12:15], off offset:256
	v_pk_mul_f32 v[6:7], v[136:137], v[6:7] op_sel_hi:[0,1]
	v_pk_mul_f32 v[4:5], v[136:137], v[4:5] op_sel_hi:[0,1]
	v_pk_mul_f32 v[14:15], v[136:137], v[18:19] op_sel_hi:[0,1]
	v_pk_mul_f32 v[18:19], v[136:137], v[10:11] op_sel_hi:[0,1]
	v_pk_mul_f32 v[10:11], v[136:137], v[8:9] op_sel_hi:[0,1]
	v_cvt_pk_bf16_f32 v8, v16, v17
	v_cvt_pk_bf16_f32 v9, v14, v15
	v_add_co_u32_e32 v14, vcc, s86, v160
	v_lshl_add_u64 v[12:13], v[160:161], 0, s[38:39]
	s_nop 0
	v_addc_co_u32_e32 v15, vcc, 0, v161, vcc
	v_cvt_pk_bf16_f32 v10, v10, v11
	v_cvt_pk_bf16_f32 v11, v18, v19
	global_store_dwordx4 v[14:15], v[8:11], off
	s_and_b64 vcc, s[8:9], exec
	s_nop 0
	v_pk_mul_f32 v[8:9], v[136:137], v[2:3] op_sel_hi:[0,1]
	v_pk_mul_f32 v[2:3], v[136:137], v[0:1] op_sel_hi:[0,1]
	v_cvt_pk_bf16_f32 v0, v4, v5
	v_cvt_pk_bf16_f32 v1, v6, v7
	v_cvt_pk_bf16_f32 v2, v2, v3
	v_cvt_pk_bf16_f32 v3, v8, v9
	global_store_dwordx4 v[12:13], v[0:3], off offset:256
	s_cbranch_vccz .LBB0_315
	s_nop 0
	v_lshl_add_u32 v0, s87, 8, v137
	v_ashrrev_i32_e32 v1, 31, v0
	v_lshl_add_u64 v[0:1], v[0:1], 2, s[34:35]
	global_load_dword v158, v[0:1], off
	global_load_dword v156, v[0:1], off offset:64
	global_load_dword v154, v[0:1], off offset:128
	global_load_dword v152, v[0:1], off offset:192
	global_load_dword v150, v[0:1], off offset:512
	global_load_dword v140, v[0:1], off offset:576
	global_load_dword v138, v[0:1], off offset:640
	global_load_dword v136, v[0:1], off offset:704
	s_mov_b64 s[46:47], 0
	s_branch .LBB0_315

.LBB0_514:
	ds_read_b128 v[128:131], v171
	ds_read_b128 v[132:135], v171 offset:1024
	ds_read_b128 v[136:139], v171 offset:2048
	ds_read_b128 v[140:143], v171 offset:3072
	s_add_u32 s40, s38, 0xfff00080
	s_addc_u32 s41, s39, -1
	s_cmp_eq_u32 s61, 60
	s_cselect_b32 s43, s6, s41
	s_cselect_b32 s42, s7, s40
	s_cselect_b32 s41, s25, s55
	s_cselect_b32 s40, s27, s35
	v_lshl_add_u64 v[202:203], s[38:39], 0, v[152:153]
	s_add_i32 m0, s37, 0xc000
	ds_read_b128 v[160:163], v173
	ds_read_b128 v[164:167], v173 offset:1024
	ds_read_b128 v[176:179], v173 offset:2048
	ds_read_b128 v[180:183], v173 offset:3072
	ds_read_b128 v[186:189], v173 offset:4096
	ds_read_b128 v[190:193], v173 offset:5120
	ds_read_b128 v[194:197], v173 offset:6144
	ds_read_b128 v[198:201], v173 offset:7168
	global_load_lds_dwordx4 v[202:203], off
	s_add_i32 m0, s37, 0xe000
	v_lshl_add_u64 v[202:203], s[38:39], 0, v[154:155]
	global_load_lds_dwordx4 v[202:203], off
	s_waitcnt lgkmcnt(8)
	s_barrier
	s_waitcnt lgkmcnt(0)
	v_mfma_f32_16x16x32_bf16 v[124:127], v[128:131], v[160:163], v[124:127]
	v_mfma_f32_16x16x32_bf16 v[124:127], v[132:135], v[164:167], v[124:127]
	v_mfma_f32_16x16x32_bf16 v[120:123], v[136:139], v[160:163], v[120:123]
	v_mfma_f32_16x16x32_bf16 v[120:123], v[140:143], v[164:167], v[120:123]
	v_mfma_f32_16x16x32_bf16 v[108:111], v[128:131], v[176:179], v[108:111]
	v_mfma_f32_16x16x32_bf16 v[108:111], v[132:135], v[180:183], v[108:111]
	v_mfma_f32_16x16x32_bf16 v[104:107], v[136:139], v[176:179], v[104:107]
	v_mfma_f32_16x16x32_bf16 v[104:107], v[140:143], v[180:183], v[104:107]
	v_mfma_f32_16x16x32_bf16 v[92:95], v[128:131], v[186:189], v[92:95]
	v_mfma_f32_16x16x32_bf16 v[92:95], v[132:135], v[190:193], v[92:95]
	v_mfma_f32_16x16x32_bf16 v[88:91], v[136:139], v[186:189], v[88:91]
	v_mfma_f32_16x16x32_bf16 v[88:91], v[140:143], v[190:193], v[88:91]
	v_mfma_f32_16x16x32_bf16 v[76:79], v[128:131], v[194:197], v[76:79]
	v_mfma_f32_16x16x32_bf16 v[76:79], v[132:135], v[198:201], v[76:79]
	v_mfma_f32_16x16x32_bf16 v[72:75], v[136:139], v[194:197], v[72:75]
	v_mfma_f32_16x16x32_bf16 v[72:75], v[140:143], v[198:201], v[72:75]
	s_barrier
	s_add_i32 s62, s53, s5
	v_lshl_add_u64 v[218:219], s[40:41], 0, v[146:147]
	s_mov_b32 m0, s62
	ds_read_b128 v[202:205], v174
	ds_read_b128 v[206:209], v174 offset:1024
	ds_read_b128 v[210:213], v174 offset:2048
	ds_read_b128 v[214:217], v174 offset:3072
	global_load_lds_dwordx4 v[218:219], off
	s_add_i32 m0, s62, 0x2000
	v_lshl_add_u64 v[220:221], s[40:41], 0, v[150:151]
	global_load_lds_dwordx4 v[220:221], off
	s_barrier
	s_waitcnt lgkmcnt(0)
	v_mfma_f32_16x16x32_bf16 v[116:119], v[202:205], v[160:163], v[116:119]
	v_mfma_f32_16x16x32_bf16 v[116:119], v[206:209], v[164:167], v[116:119]
	v_mfma_f32_16x16x32_bf16 v[112:115], v[210:213], v[160:163], v[112:115]
	v_mfma_f32_16x16x32_bf16 v[112:115], v[214:217], v[164:167], v[112:115]
	v_mfma_f32_16x16x32_bf16 v[100:103], v[202:205], v[176:179], v[100:103]
	v_mfma_f32_16x16x32_bf16 v[100:103], v[206:209], v[180:183], v[100:103]
	v_mfma_f32_16x16x32_bf16 v[96:99], v[210:213], v[176:179], v[96:99]
	v_mfma_f32_16x16x32_bf16 v[96:99], v[214:217], v[180:183], v[96:99]
	v_mfma_f32_16x16x32_bf16 v[84:87], v[202:205], v[186:189], v[84:87]
	v_mfma_f32_16x16x32_bf16 v[84:87], v[206:209], v[190:193], v[84:87]
	v_mfma_f32_16x16x32_bf16 v[80:83], v[210:213], v[186:189], v[80:83]
	v_mfma_f32_16x16x32_bf16 v[80:83], v[214:217], v[190:193], v[80:83]
	v_mfma_f32_16x16x32_bf16 v[68:71], v[202:205], v[194:197], v[68:71]
	v_mfma_f32_16x16x32_bf16 v[68:71], v[206:209], v[198:201], v[68:71]
	v_mfma_f32_16x16x32_bf16 v[64:67], v[210:213], v[194:197], v[64:67]
	v_mfma_f32_16x16x32_bf16 v[64:67], v[214:217], v[198:201], v[64:67]
	s_mov_b32 m0, s37
	v_lshl_add_u64 v[222:223], s[42:43], 0, v[144:145]
	s_barrier
	ds_read_b128 v[160:163], v173 offset:16384
	ds_read_b128 v[164:167], v173 offset:17408
	ds_read_b128 v[176:179], v173 offset:18432
	ds_read_b128 v[180:183], v173 offset:19456
	ds_read_b128 v[186:189], v173 offset:20480
	ds_read_b128 v[190:193], v173 offset:21504
	ds_read_b128 v[194:197], v173 offset:22528
	ds_read_b128 v[198:201], v173 offset:23552
	global_load_lds_dwordx4 v[222:223], off
	s_mov_b32 m0, s44
	v_lshl_add_u64 v[224:225], s[42:43], 0, v[148:149]
	global_load_lds_dwordx4 v[224:225], off
	s_barrier
	s_waitcnt lgkmcnt(0)
	v_mfma_f32_16x16x32_bf16 v[60:63], v[128:131], v[160:163], v[60:63]
	v_mfma_f32_16x16x32_bf16 v[60:63], v[132:135], v[164:167], v[60:63]
	v_mfma_f32_16x16x32_bf16 v[56:59], v[136:139], v[160:163], v[56:59]
	v_mfma_f32_16x16x32_bf16 v[56:59], v[140:143], v[164:167], v[56:59]
	v_mfma_f32_16x16x32_bf16 v[44:47], v[128:131], v[176:179], v[44:47]
	v_mfma_f32_16x16x32_bf16 v[44:47], v[132:135], v[180:183], v[44:47]
	v_mfma_f32_16x16x32_bf16 v[40:43], v[136:139], v[176:179], v[40:43]
	v_mfma_f32_16x16x32_bf16 v[40:43], v[140:143], v[180:183], v[40:43]
	v_mfma_f32_16x16x32_bf16 v[28:31], v[128:131], v[186:189], v[28:31]
	v_mfma_f32_16x16x32_bf16 v[28:31], v[132:135], v[190:193], v[28:31]
	v_mfma_f32_16x16x32_bf16 v[24:27], v[136:139], v[186:189], v[24:27]
	v_mfma_f32_16x16x32_bf16 v[24:27], v[140:143], v[190:193], v[24:27]
	v_mfma_f32_16x16x32_bf16 v[12:15], v[128:131], v[194:197], v[12:15]
	v_mfma_f32_16x16x32_bf16 v[12:15], v[132:135], v[198:201], v[12:15]
	v_mfma_f32_16x16x32_bf16 v[8:11], v[136:139], v[194:197], v[8:11]
	v_mfma_f32_16x16x32_bf16 v[8:11], v[140:143], v[198:201], v[8:11]
	s_barrier
	s_add_u32 s62, s40, 0x100000
	s_addc_u32 s63, s41, 0
	s_add_i32 s74, s54, s5
	s_mov_b32 m0, s74
	v_lshl_add_u64 v[128:129], s[62:63], 0, v[146:147]
	global_load_lds_dwordx4 v[128:129], off
	s_add_i32 m0, s74, 0x2000
	v_lshl_add_u64 v[128:129], s[62:63], 0, v[150:151]
	global_load_lds_dwordx4 v[128:129], off
	s_waitcnt vmcnt(6)
	s_barrier
	v_mfma_f32_16x16x32_bf16 v[52:55], v[202:205], v[160:163], v[52:55]
	v_mfma_f32_16x16x32_bf16 v[52:55], v[206:209], v[164:167], v[52:55]
	v_mfma_f32_16x16x32_bf16 v[48:51], v[210:213], v[160:163], v[48:51]
	v_mfma_f32_16x16x32_bf16 v[48:51], v[214:217], v[164:167], v[48:51]
	v_mfma_f32_16x16x32_bf16 v[36:39], v[202:205], v[176:179], v[36:39]
	v_mfma_f32_16x16x32_bf16 v[36:39], v[206:209], v[180:183], v[36:39]
	v_mfma_f32_16x16x32_bf16 v[32:35], v[210:213], v[176:179], v[32:35]
	v_mfma_f32_16x16x32_bf16 v[32:35], v[214:217], v[180:183], v[32:35]
	v_mfma_f32_16x16x32_bf16 v[20:23], v[202:205], v[186:189], v[20:23]
	v_mfma_f32_16x16x32_bf16 v[20:23], v[206:209], v[190:193], v[20:23]
	v_mfma_f32_16x16x32_bf16 v[16:19], v[210:213], v[186:189], v[16:19]
	v_mfma_f32_16x16x32_bf16 v[16:19], v[214:217], v[190:193], v[16:19]
	v_mfma_f32_16x16x32_bf16 v[4:7], v[202:205], v[194:197], v[4:7]
	v_mfma_f32_16x16x32_bf16 v[4:7], v[206:209], v[198:201], v[4:7]
	v_mfma_f32_16x16x32_bf16 v[0:3], v[210:213], v[194:197], v[0:3]
	v_mfma_f32_16x16x32_bf16 v[0:3], v[214:217], v[198:201], v[0:3]
	s_add_i32 s62, 0, 0x18000
	v_add_u32_e32 v140, s62, v169
	s_barrier
	ds_read_b128 v[128:131], v140
	ds_read_b128 v[132:135], v140 offset:1024
	ds_read_b128 v[136:139], v140 offset:2048
	ds_read_b128 v[140:143], v140 offset:3072
	s_add_u32 s42, s42, 0x100000
	s_addc_u32 s43, s43, 0
	s_mov_b32 m0, s45
	v_lshl_add_u64 v[202:203], s[42:43], 0, v[144:145]
	ds_read_b128 v[160:163], v173 offset:32768
	ds_read_b128 v[164:167], v173 offset:33792
	ds_read_b128 v[176:179], v173 offset:34816
	ds_read_b128 v[180:183], v173 offset:35840
	ds_read_b128 v[186:189], v173 offset:36864
	ds_read_b128 v[190:193], v173 offset:37888
	ds_read_b128 v[194:197], v173 offset:38912
	ds_read_b128 v[198:201], v173 offset:39936
	global_load_lds_dwordx4 v[202:203], off
	s_mov_b32 m0, s46
	v_lshl_add_u64 v[202:203], s[42:43], 0, v[148:149]
	global_load_lds_dwordx4 v[202:203], off
	s_waitcnt lgkmcnt(8)
	s_barrier
	s_waitcnt lgkmcnt(0)
	v_mfma_f32_16x16x32_bf16 v[124:127], v[128:131], v[160:163], v[124:127]
	v_mfma_f32_16x16x32_bf16 v[124:127], v[132:135], v[164:167], v[124:127]
	v_mfma_f32_16x16x32_bf16 v[120:123], v[136:139], v[160:163], v[120:123]
	v_mfma_f32_16x16x32_bf16 v[120:123], v[140:143], v[164:167], v[120:123]
	v_mfma_f32_16x16x32_bf16 v[108:111], v[128:131], v[176:179], v[108:111]
	v_mfma_f32_16x16x32_bf16 v[108:111], v[132:135], v[180:183], v[108:111]
	v_mfma_f32_16x16x32_bf16 v[104:107], v[136:139], v[176:179], v[104:107]
	v_mfma_f32_16x16x32_bf16 v[104:107], v[140:143], v[180:183], v[104:107]
	v_mfma_f32_16x16x32_bf16 v[92:95], v[128:131], v[186:189], v[92:95]
	v_mfma_f32_16x16x32_bf16 v[92:95], v[132:135], v[190:193], v[92:95]
	v_mfma_f32_16x16x32_bf16 v[88:91], v[136:139], v[186:189], v[88:91]
	v_mfma_f32_16x16x32_bf16 v[88:91], v[140:143], v[190:193], v[88:91]
	v_mfma_f32_16x16x32_bf16 v[76:79], v[128:131], v[194:197], v[76:79]
	v_mfma_f32_16x16x32_bf16 v[76:79], v[132:135], v[198:201], v[76:79]
	v_mfma_f32_16x16x32_bf16 v[72:75], v[136:139], v[194:197], v[72:75]
	v_mfma_f32_16x16x32_bf16 v[72:75], v[140:143], v[198:201], v[72:75]
	s_barrier
	s_add_i32 s42, 0, 0x1c000
	s_add_i32 s43, s62, s5
	v_add_u32_e32 v185, s42, v169
	v_lshl_add_u64 v[218:219], v[218:219], 0, s[22:23]
	s_mov_b32 m0, s43
	ds_read_b128 v[202:205], v185
	ds_read_b128 v[206:209], v185 offset:1024
	ds_read_b128 v[210:213], v185 offset:2048
	ds_read_b128 v[214:217], v185 offset:3072
	global_load_lds_dwordx4 v[218:219], off
	s_add_i32 m0, s43, 0x2000
	v_lshl_add_u64 v[218:219], v[220:221], 0, s[22:23]
	global_load_lds_dwordx4 v[218:219], off
	s_barrier
	s_waitcnt lgkmcnt(0)
	v_mfma_f32_16x16x32_bf16 v[116:119], v[202:205], v[160:163], v[116:119]
	v_mfma_f32_16x16x32_bf16 v[116:119], v[206:209], v[164:167], v[116:119]
	v_mfma_f32_16x16x32_bf16 v[112:115], v[210:213], v[160:163], v[112:115]
	v_mfma_f32_16x16x32_bf16 v[112:115], v[214:217], v[164:167], v[112:115]
	v_mfma_f32_16x16x32_bf16 v[100:103], v[202:205], v[176:179], v[100:103]
	v_mfma_f32_16x16x32_bf16 v[100:103], v[206:209], v[180:183], v[100:103]
	v_mfma_f32_16x16x32_bf16 v[96:99], v[210:213], v[176:179], v[96:99]
	v_mfma_f32_16x16x32_bf16 v[96:99], v[214:217], v[180:183], v[96:99]
	v_mfma_f32_16x16x32_bf16 v[84:87], v[202:205], v[186:189], v[84:87]
	v_mfma_f32_16x16x32_bf16 v[84:87], v[206:209], v[190:193], v[84:87]
	v_mfma_f32_16x16x32_bf16 v[80:83], v[210:213], v[186:189], v[80:83]
	v_mfma_f32_16x16x32_bf16 v[80:83], v[214:217], v[190:193], v[80:83]
	v_mfma_f32_16x16x32_bf16 v[68:71], v[202:205], v[194:197], v[68:71]
	v_mfma_f32_16x16x32_bf16 v[68:71], v[206:209], v[198:201], v[68:71]
	v_mfma_f32_16x16x32_bf16 v[64:67], v[210:213], v[194:197], v[64:67]
	v_mfma_f32_16x16x32_bf16 v[64:67], v[214:217], v[198:201], v[64:67]
	s_mov_b32 m0, s48
	v_lshl_add_u64 v[218:219], v[222:223], 0, s[22:23]
	s_barrier
	ds_read_b128 v[160:163], v173 offset:49152
	ds_read_b128 v[164:167], v173 offset:50176
	ds_read_b128 v[176:179], v173 offset:51200
	ds_read_b128 v[180:183], v173 offset:52224
	ds_read_b128 v[186:189], v173 offset:53248
	ds_read_b128 v[190:193], v173 offset:54272
	ds_read_b128 v[194:197], v173 offset:55296
	ds_read_b128 v[198:201], v173 offset:56320
	global_load_lds_dwordx4 v[218:219], off
	s_mov_b32 m0, s49
	v_lshl_add_u64 v[218:219], v[224:225], 0, s[22:23]
	global_load_lds_dwordx4 v[218:219], off
	s_barrier
	s_waitcnt lgkmcnt(0)
	v_mfma_f32_16x16x32_bf16 v[60:63], v[128:131], v[160:163], v[60:63]
	v_mfma_f32_16x16x32_bf16 v[60:63], v[132:135], v[164:167], v[60:63]
	v_mfma_f32_16x16x32_bf16 v[56:59], v[136:139], v[160:163], v[56:59]
	v_mfma_f32_16x16x32_bf16 v[56:59], v[140:143], v[164:167], v[56:59]
	v_mfma_f32_16x16x32_bf16 v[44:47], v[128:131], v[176:179], v[44:47]
	v_mfma_f32_16x16x32_bf16 v[44:47], v[132:135], v[180:183], v[44:47]
	v_mfma_f32_16x16x32_bf16 v[40:43], v[136:139], v[176:179], v[40:43]
	v_mfma_f32_16x16x32_bf16 v[40:43], v[140:143], v[180:183], v[40:43]
	v_mfma_f32_16x16x32_bf16 v[28:31], v[128:131], v[186:189], v[28:31]
	v_mfma_f32_16x16x32_bf16 v[28:31], v[132:135], v[190:193], v[28:31]
	v_mfma_f32_16x16x32_bf16 v[24:27], v[136:139], v[186:189], v[24:27]
	v_mfma_f32_16x16x32_bf16 v[24:27], v[140:143], v[190:193], v[24:27]
	v_mfma_f32_16x16x32_bf16 v[12:15], v[128:131], v[194:197], v[12:15]
	v_mfma_f32_16x16x32_bf16 v[12:15], v[132:135], v[198:201], v[12:15]
	v_mfma_f32_16x16x32_bf16 v[8:11], v[136:139], v[194:197], v[8:11]
	v_mfma_f32_16x16x32_bf16 v[8:11], v[140:143], v[198:201], v[8:11]
	s_barrier
	s_add_u32 s40, s40, 0x100080
	s_addc_u32 s41, s41, 0
	s_add_i32 s42, s42, s5
	s_mov_b32 m0, s42
	v_lshl_add_u64 v[128:129], s[40:41], 0, v[146:147]
	global_load_lds_dwordx4 v[128:129], off
	s_add_i32 m0, s42, 0x2000
	v_lshl_add_u64 v[128:129], s[40:41], 0, v[150:151]
	global_load_lds_dwordx4 v[128:129], off
	s_waitcnt vmcnt(6)
	s_barrier
	v_mfma_f32_16x16x32_bf16 v[52:55], v[202:205], v[160:163], v[52:55]
	v_mfma_f32_16x16x32_bf16 v[52:55], v[206:209], v[164:167], v[52:55]
	v_mfma_f32_16x16x32_bf16 v[48:51], v[210:213], v[160:163], v[48:51]
	v_mfma_f32_16x16x32_bf16 v[48:51], v[214:217], v[164:167], v[48:51]
	v_mfma_f32_16x16x32_bf16 v[36:39], v[202:205], v[176:179], v[36:39]
	v_mfma_f32_16x16x32_bf16 v[36:39], v[206:209], v[180:183], v[36:39]
	v_mfma_f32_16x16x32_bf16 v[32:35], v[210:213], v[176:179], v[32:35]
	v_mfma_f32_16x16x32_bf16 v[32:35], v[214:217], v[180:183], v[32:35]
	v_mfma_f32_16x16x32_bf16 v[20:23], v[202:205], v[186:189], v[20:23]
	v_mfma_f32_16x16x32_bf16 v[20:23], v[206:209], v[190:193], v[20:23]
	v_mfma_f32_16x16x32_bf16 v[16:19], v[210:213], v[186:189], v[16:19]
	v_mfma_f32_16x16x32_bf16 v[16:19], v[214:217], v[190:193], v[16:19]
	v_mfma_f32_16x16x32_bf16 v[4:7], v[202:205], v[194:197], v[4:7]
	v_mfma_f32_16x16x32_bf16 v[4:7], v[206:209], v[198:201], v[4:7]
	v_mfma_f32_16x16x32_bf16 v[0:3], v[210:213], v[194:197], v[0:3]
	v_mfma_f32_16x16x32_bf16 v[0:3], v[214:217], v[198:201], v[0:3]
	s_add_i32 s61, s61, 2
	s_add_u32 s38, s38, 0x100
	s_addc_u32 s39, s39, 0
	s_add_u32 s35, s35, 0x100
	s_addc_u32 s55, s55, 0
	s_cmp_gt_u32 s61, 61
	s_barrier
	s_cbranch_scc0 .LBB0_514
	v_lshl_add_u32 v162, s34, 8, v168
	v_lshl_or_b32 v160, s36, 8, v170
	v_ashrrev_i32_e32 v163, 31, v162
	v_ashrrev_i32_e32 v161, 31, v160
	v_lshlrev_b64 v[128:129], 14, v[162:163]
	v_lshl_add_u64 v[128:129], s[12:13], 0, v[128:129]
	v_lshlrev_b64 v[130:131], 2, v[160:161]
	v_lshl_add_u64 v[128:129], v[128:129], 0, v[130:131]
	global_load_dwordx4 v[178:181], v[128:129], off
	global_load_dwordx4 v[186:189], v[128:129], off offset:16
	global_load_dwordx4 v[190:193], v[128:129], off offset:512
	global_load_dwordx4 v[194:197], v[128:129], off offset:528
	v_or_b32_e32 v164, 16, v162
	v_ashrrev_i32_e32 v165, 31, v164
	v_lshlrev_b64 v[128:129], 14, v[164:165]
	v_lshl_add_u64 v[128:129], s[12:13], 0, v[128:129]
	v_lshl_add_u64 v[132:133], v[128:129], 0, v[130:131]
	global_load_dwordx4 v[136:139], v[132:133], off offset:16
	global_load_dwordx4 v[140:143], v[132:133], off
	global_load_dwordx4 v[128:131], v[132:133], off offset:528
	s_nop 0
	global_load_dwordx4 v[132:135], v[132:133], off offset:512
	v_and_b32_e32 v166, 64, v175
	v_xor_b32_e32 v176, 16, v175
	v_add_u32_e32 v182, 64, v166
	v_xor_b32_e32 v177, 32, v175
	v_cmp_lt_i32_e32 vcc, v176, v182
	v_lshlrev_b64 v[166:167], 13, v[162:163]
	v_lshl_add_u64 v[166:167], s[56:57], 0, v[166:167]
	v_cndmask_b32_e32 v176, v175, v176, vcc
	v_cmp_lt_i32_e32 vcc, v177, v182
	v_lshlrev_b32_e32 v176, 2, v176
	v_lshl_add_u64 v[166:167], v[160:161], 1, v[166:167]
	v_cndmask_b32_e32 v177, v175, v177, vcc
	v_lshlrev_b32_e32 v177, 2, v177
	s_waitcnt vmcnt(0)
	v_pk_add_f32 v[126:127], v[126:127], v[180:181]
	v_pk_add_f32 v[124:125], v[124:125], v[178:179]
	v_pk_add_f32 v[118:119], v[118:119], v[192:193]
	v_pk_add_f32 v[116:117], v[116:117], v[190:191]
	v_pk_add_f32 v[120:121], v[120:121], v[186:187]
	v_pk_add_f32 v[178:179], v[114:115], v[196:197]
	v_pk_add_f32 v[180:181], v[112:113], v[194:195]
	v_mul_f32_e32 v114, v125, v125
	v_mul_f32_e32 v115, v127, v127
	v_cvt_pk_bf16_f32 v112, v124, v125
	v_cvt_pk_bf16_f32 v113, v126, v127
	v_mul_f32_e32 v125, v117, v117
	v_mul_f32_e32 v127, v119, v119
	v_pk_add_f32 v[122:123], v[122:123], v[188:189]
	v_mul_f32_e32 v182, v121, v121
	v_mul_f32_e32 v185, v181, v181
	v_fmac_f32_e32 v114, v124, v124
	v_fmac_f32_e32 v115, v126, v126
	v_fmac_f32_e32 v125, v116, v116
	v_fmac_f32_e32 v127, v118, v118
	v_mul_f32_e32 v183, v123, v123
	v_mul_f32_e32 v186, v179, v179
	v_fmac_f32_e32 v182, v120, v120
	v_fmac_f32_e32 v185, v180, v180
	v_add_f32_e32 v114, v114, v115
	v_add_f32_e32 v115, v125, v127
	v_fmac_f32_e32 v183, v122, v122
	v_fmac_f32_e32 v186, v178, v178
	v_add_f32_e32 v114, v114, v182
	v_add_f32_e32 v115, v115, v185
	v_add_f32_e32 v114, v183, v114
	v_add_f32_e32 v115, v186, v115
	v_add_f32_e32 v124, v114, v115
	ds_bpermute_b32 v125, v176, v124
	v_cvt_pk_bf16_f32 v114, v120, v121
	v_cvt_pk_bf16_f32 v115, v122, v123
	global_store_dwordx4 v[166:167], v[112:115], off
	s_waitcnt lgkmcnt(0)
	s_nop 0
	v_add_f32_e32 v112, v124, v125
	ds_bpermute_b32 v113, v177, v112
	v_cvt_pk_bf16_f32 v114, v116, v117
	v_cvt_pk_bf16_f32 v115, v118, v119
	v_cvt_pk_bf16_f32 v116, v180, v181
	v_cvt_pk_bf16_f32 v117, v178, v179
	global_store_dwordx4 v[166:167], v[114:117], off offset:256
	s_and_saveexec_b64 s[34:35], s[8:9]
	s_cbranch_execz .LBB0_517
	v_lshl_add_u64 v[114:115], v[162:163], 2, s[20:21]
	s_waitcnt lgkmcnt(0)
	v_add_f32_e32 v112, v112, v113
	global_atomic_add_f32 v[114:115], v112, off

.LBB0_604:
	ds_read_b128 v[16:19], v176
	ds_read_b128 v[20:23], v176 offset:1024
	ds_read_b128 v[32:35], v176 offset:2048
	ds_read_b128 v[36:39], v176 offset:3072
	s_add_u32 s41, s10, 0xfff00080
	s_addc_u32 s46, s11, -1
	s_cmp_eq_u32 s39, 60
	s_cselect_b32 s49, s4, s46
	s_cselect_b32 s48, s5, s41
	s_cselect_b32 s47, s6, s15
	s_cselect_b32 s46, s7, s13
	v_lshl_add_u64 v[160:161], s[10:11], 0, v[152:153]
	s_add_i32 m0, s52, 0xc000
	ds_read_b128 v[164:167], v177
	ds_read_b128 v[168:171], v177 offset:1024
	ds_read_b128 v[190:193], v177 offset:2048
	ds_read_b128 v[194:197], v177 offset:3072
	ds_read_b128 v[198:201], v177 offset:4096
	ds_read_b128 v[202:205], v177 offset:5120
	ds_read_b128 v[206:209], v177 offset:6144
	ds_read_b128 v[210:213], v177 offset:7168
	global_load_lds_dwordx4 v[160:161], off
	s_add_i32 m0, s52, 0xe000
	v_lshl_add_u64 v[160:161], s[10:11], 0, v[154:155]
	global_load_lds_dwordx4 v[160:161], off
	s_waitcnt lgkmcnt(8)
	s_barrier
	s_waitcnt lgkmcnt(0)
	v_mfma_f32_16x16x32_bf16 v[140:143], v[16:19], v[164:167], v[140:143]
	v_mfma_f32_16x16x32_bf16 v[140:143], v[20:23], v[168:171], v[140:143]
	v_mfma_f32_16x16x32_bf16 v[136:139], v[32:35], v[164:167], v[136:139]
	v_mfma_f32_16x16x32_bf16 v[136:139], v[36:39], v[168:171], v[136:139]
	v_mfma_f32_16x16x32_bf16 v[124:127], v[16:19], v[190:193], v[124:127]
	v_mfma_f32_16x16x32_bf16 v[124:127], v[20:23], v[194:197], v[124:127]
	v_mfma_f32_16x16x32_bf16 v[120:123], v[32:35], v[190:193], v[120:123]
	v_mfma_f32_16x16x32_bf16 v[120:123], v[36:39], v[194:197], v[120:123]
	v_mfma_f32_16x16x32_bf16 v[108:111], v[16:19], v[198:201], v[108:111]
	v_mfma_f32_16x16x32_bf16 v[108:111], v[20:23], v[202:205], v[108:111]
	v_mfma_f32_16x16x32_bf16 v[104:107], v[32:35], v[198:201], v[104:107]
	v_mfma_f32_16x16x32_bf16 v[104:107], v[36:39], v[202:205], v[104:107]
	v_mfma_f32_16x16x32_bf16 v[92:95], v[16:19], v[206:209], v[92:95]
	v_mfma_f32_16x16x32_bf16 v[92:95], v[20:23], v[210:213], v[92:95]
	v_mfma_f32_16x16x32_bf16 v[88:91], v[32:35], v[206:209], v[88:91]
	v_mfma_f32_16x16x32_bf16 v[88:91], v[36:39], v[210:213], v[88:91]
	s_barrier
	s_add_i32 s41, s81, s51
	v_lshl_add_u64 v[160:161], s[46:47], 0, v[146:147]
	s_mov_b32 m0, s41
	ds_read_b128 v[214:217], v178
	ds_read_b128 v[218:221], v178 offset:1024
	ds_read_b128 v[222:225], v178 offset:2048
	ds_read_b128 v[226:229], v178 offset:3072
	global_load_lds_dwordx4 v[160:161], off
	s_add_i32 m0, s41, 0x2000
	v_lshl_add_u64 v[230:231], s[46:47], 0, v[150:151]
	global_load_lds_dwordx4 v[230:231], off
	s_barrier
	s_waitcnt lgkmcnt(0)
	v_mfma_f32_16x16x32_bf16 v[132:135], v[214:217], v[164:167], v[132:135]
	v_mfma_f32_16x16x32_bf16 v[132:135], v[218:221], v[168:171], v[132:135]
	v_mfma_f32_16x16x32_bf16 v[128:131], v[222:225], v[164:167], v[128:131]
	v_mfma_f32_16x16x32_bf16 v[128:131], v[226:229], v[168:171], v[128:131]
	v_mfma_f32_16x16x32_bf16 v[116:119], v[214:217], v[190:193], v[116:119]
	v_mfma_f32_16x16x32_bf16 v[116:119], v[218:221], v[194:197], v[116:119]
	v_mfma_f32_16x16x32_bf16 v[112:115], v[222:225], v[190:193], v[112:115]
	v_mfma_f32_16x16x32_bf16 v[112:115], v[226:229], v[194:197], v[112:115]
	v_mfma_f32_16x16x32_bf16 v[100:103], v[214:217], v[198:201], v[100:103]
	v_mfma_f32_16x16x32_bf16 v[100:103], v[218:221], v[202:205], v[100:103]
	v_mfma_f32_16x16x32_bf16 v[96:99], v[222:225], v[198:201], v[96:99]
	v_mfma_f32_16x16x32_bf16 v[96:99], v[226:229], v[202:205], v[96:99]
	v_mfma_f32_16x16x32_bf16 v[84:87], v[214:217], v[206:209], v[84:87]
	v_mfma_f32_16x16x32_bf16 v[84:87], v[218:221], v[210:213], v[84:87]
	v_mfma_f32_16x16x32_bf16 v[80:83], v[222:225], v[206:209], v[80:83]
	v_mfma_f32_16x16x32_bf16 v[80:83], v[226:229], v[210:213], v[80:83]
	s_mov_b32 m0, s52
	v_lshl_add_u64 v[232:233], s[48:49], 0, v[144:145]
	s_barrier
	ds_read_b128 v[164:167], v177 offset:16384
	ds_read_b128 v[168:171], v177 offset:17408
	ds_read_b128 v[190:193], v177 offset:18432
	ds_read_b128 v[194:197], v177 offset:19456
	ds_read_b128 v[198:201], v177 offset:20480
	ds_read_b128 v[202:205], v177 offset:21504
	ds_read_b128 v[206:209], v177 offset:22528
	ds_read_b128 v[210:213], v177 offset:23552
	global_load_lds_dwordx4 v[232:233], off
	s_mov_b32 m0, s53
	v_lshl_add_u64 v[234:235], s[48:49], 0, v[148:149]
	global_load_lds_dwordx4 v[234:235], off
	s_barrier
	s_waitcnt lgkmcnt(0)
	v_mfma_f32_16x16x32_bf16 v[76:79], v[16:19], v[164:167], v[76:79]
	v_mfma_f32_16x16x32_bf16 v[76:79], v[20:23], v[168:171], v[76:79]
	v_mfma_f32_16x16x32_bf16 v[72:75], v[32:35], v[164:167], v[72:75]
	v_mfma_f32_16x16x32_bf16 v[72:75], v[36:39], v[168:171], v[72:75]
	v_mfma_f32_16x16x32_bf16 v[60:63], v[16:19], v[190:193], v[60:63]
	v_mfma_f32_16x16x32_bf16 v[60:63], v[20:23], v[194:197], v[60:63]
	v_mfma_f32_16x16x32_bf16 v[56:59], v[32:35], v[190:193], v[56:59]
	v_mfma_f32_16x16x32_bf16 v[56:59], v[36:39], v[194:197], v[56:59]
	v_mfma_f32_16x16x32_bf16 v[44:47], v[16:19], v[198:201], v[44:47]
	v_mfma_f32_16x16x32_bf16 v[44:47], v[20:23], v[202:205], v[44:47]
	v_mfma_f32_16x16x32_bf16 v[40:43], v[32:35], v[198:201], v[40:43]
	v_mfma_f32_16x16x32_bf16 v[40:43], v[36:39], v[202:205], v[40:43]
	v_mfma_f32_16x16x32_bf16 v[12:15], v[16:19], v[206:209], v[12:15]
	v_mfma_f32_16x16x32_bf16 v[12:15], v[20:23], v[210:213], v[12:15]
	v_mfma_f32_16x16x32_bf16 v[8:11], v[32:35], v[206:209], v[8:11]
	v_mfma_f32_16x16x32_bf16 v[8:11], v[36:39], v[210:213], v[8:11]
	s_barrier
	s_add_u32 s54, s46, 0x100000
	s_addc_u32 s55, s47, 0
	s_add_i32 s41, s82, s51
	s_mov_b32 m0, s41
	v_lshl_add_u64 v[16:17], s[54:55], 0, v[146:147]
	global_load_lds_dwordx4 v[16:17], off
	s_add_i32 m0, s41, 0x2000
	v_lshl_add_u64 v[16:17], s[54:55], 0, v[150:151]
	global_load_lds_dwordx4 v[16:17], off
	s_waitcnt vmcnt(6)
	s_barrier
	v_mfma_f32_16x16x32_bf16 v[28:31], v[214:217], v[198:201], v[28:31]
	v_mfma_f32_16x16x32_bf16 v[28:31], v[218:221], v[202:205], v[28:31]
	v_mfma_f32_16x16x32_bf16 v[24:27], v[222:225], v[198:201], v[24:27]
	v_mfma_f32_16x16x32_bf16 v[24:27], v[226:229], v[202:205], v[24:27]
	v_mfma_f32_16x16x32_bf16 v[4:7], v[214:217], v[206:209], v[4:7]
	v_mfma_f32_16x16x32_bf16 v[4:7], v[218:221], v[210:213], v[4:7]
	v_mfma_f32_16x16x32_bf16 v[0:3], v[222:225], v[206:209], v[0:3]
	v_mfma_f32_16x16x32_bf16 v[0:3], v[226:229], v[210:213], v[0:3]
	v_mfma_f32_16x16x32_bf16 v[16:19], v[214:217], v[164:167], v[68:71]
	v_mfma_f32_16x16x32_bf16 v[16:19], v[218:221], v[168:171], v[16:19]
	v_mfma_f32_16x16x32_bf16 v[20:23], v[222:225], v[164:167], v[64:67]
	v_mfma_f32_16x16x32_bf16 v[20:23], v[226:229], v[168:171], v[20:23]
	v_mfma_f32_16x16x32_bf16 v[32:35], v[214:217], v[190:193], v[52:55]
	v_mfma_f32_16x16x32_bf16 v[32:35], v[218:221], v[194:197], v[32:35]
	v_mfma_f32_16x16x32_bf16 v[36:39], v[222:225], v[190:193], v[48:51]
	v_mfma_f32_16x16x32_bf16 v[36:39], v[226:229], v[194:197], v[36:39]
	s_add_i32 s41, 0, 0x18000
	v_add_u32_e32 v68, s41, v174
	s_barrier
	ds_read_b128 v[48:51], v68
	ds_read_b128 v[52:55], v68 offset:1024
	ds_read_b128 v[64:67], v68 offset:2048
	ds_read_b128 v[68:71], v68 offset:3072
	s_add_u32 s48, s48, 0x100000
	s_addc_u32 s49, s49, 0
	s_mov_b32 m0, s61
	v_lshl_add_u64 v[214:215], s[48:49], 0, v[144:145]
	ds_read_b128 v[164:167], v177 offset:32768
	ds_read_b128 v[168:171], v177 offset:33792
	ds_read_b128 v[190:193], v177 offset:34816
	ds_read_b128 v[194:197], v177 offset:35840
	ds_read_b128 v[198:201], v177 offset:36864
	ds_read_b128 v[202:205], v177 offset:37888
	ds_read_b128 v[206:209], v177 offset:38912
	ds_read_b128 v[210:213], v177 offset:39936
	global_load_lds_dwordx4 v[214:215], off
	s_mov_b32 m0, s74
	v_lshl_add_u64 v[214:215], s[48:49], 0, v[148:149]
	global_load_lds_dwordx4 v[214:215], off
	s_waitcnt lgkmcnt(8)
	s_barrier
	s_waitcnt lgkmcnt(0)
	v_mfma_f32_16x16x32_bf16 v[140:143], v[48:51], v[164:167], v[140:143]
	v_mfma_f32_16x16x32_bf16 v[140:143], v[52:55], v[168:171], v[140:143]
	v_mfma_f32_16x16x32_bf16 v[136:139], v[64:67], v[164:167], v[136:139]
	v_mfma_f32_16x16x32_bf16 v[136:139], v[68:71], v[168:171], v[136:139]
	v_mfma_f32_16x16x32_bf16 v[124:127], v[48:51], v[190:193], v[124:127]
	v_mfma_f32_16x16x32_bf16 v[124:127], v[52:55], v[194:197], v[124:127]
	v_mfma_f32_16x16x32_bf16 v[120:123], v[64:67], v[190:193], v[120:123]
	v_mfma_f32_16x16x32_bf16 v[120:123], v[68:71], v[194:197], v[120:123]
	v_mfma_f32_16x16x32_bf16 v[108:111], v[48:51], v[198:201], v[108:111]
	v_mfma_f32_16x16x32_bf16 v[108:111], v[52:55], v[202:205], v[108:111]
	v_mfma_f32_16x16x32_bf16 v[104:107], v[64:67], v[198:201], v[104:107]
	v_mfma_f32_16x16x32_bf16 v[104:107], v[68:71], v[202:205], v[104:107]
	v_mfma_f32_16x16x32_bf16 v[92:95], v[48:51], v[206:209], v[92:95]
	v_mfma_f32_16x16x32_bf16 v[92:95], v[52:55], v[210:213], v[92:95]
	v_mfma_f32_16x16x32_bf16 v[88:91], v[64:67], v[206:209], v[88:91]
	v_mfma_f32_16x16x32_bf16 v[88:91], v[68:71], v[210:213], v[88:91]
	s_barrier
	s_add_i32 s48, 0, 0x1c000
	s_add_i32 s41, s41, s51
	v_add_u32_e32 v163, s48, v174
	v_lshl_add_u64 v[160:161], v[160:161], 0, s[22:23]
	s_mov_b32 m0, s41
	ds_read_b128 v[214:217], v163
	ds_read_b128 v[218:221], v163 offset:1024
	ds_read_b128 v[222:225], v163 offset:2048
	ds_read_b128 v[226:229], v163 offset:3072
	global_load_lds_dwordx4 v[160:161], off
	s_add_i32 m0, s41, 0x2000
	v_lshl_add_u64 v[160:161], v[230:231], 0, s[22:23]
	global_load_lds_dwordx4 v[160:161], off
	s_barrier
	s_waitcnt lgkmcnt(0)
	v_mfma_f32_16x16x32_bf16 v[132:135], v[214:217], v[164:167], v[132:135]
	v_mfma_f32_16x16x32_bf16 v[132:135], v[218:221], v[168:171], v[132:135]
	v_mfma_f32_16x16x32_bf16 v[128:131], v[222:225], v[164:167], v[128:131]
	v_mfma_f32_16x16x32_bf16 v[128:131], v[226:229], v[168:171], v[128:131]
	v_mfma_f32_16x16x32_bf16 v[116:119], v[214:217], v[190:193], v[116:119]
	v_mfma_f32_16x16x32_bf16 v[116:119], v[218:221], v[194:197], v[116:119]
	v_mfma_f32_16x16x32_bf16 v[112:115], v[222:225], v[190:193], v[112:115]
	v_mfma_f32_16x16x32_bf16 v[112:115], v[226:229], v[194:197], v[112:115]
	v_mfma_f32_16x16x32_bf16 v[100:103], v[214:217], v[198:201], v[100:103]
	v_mfma_f32_16x16x32_bf16 v[100:103], v[218:221], v[202:205], v[100:103]
	v_mfma_f32_16x16x32_bf16 v[96:99], v[222:225], v[198:201], v[96:99]
	v_mfma_f32_16x16x32_bf16 v[96:99], v[226:229], v[202:205], v[96:99]
	v_mfma_f32_16x16x32_bf16 v[84:87], v[214:217], v[206:209], v[84:87]
	v_mfma_f32_16x16x32_bf16 v[84:87], v[218:221], v[210:213], v[84:87]
	v_mfma_f32_16x16x32_bf16 v[80:83], v[222:225], v[206:209], v[80:83]
	v_mfma_f32_16x16x32_bf16 v[80:83], v[226:229], v[210:213], v[80:83]
	s_mov_b32 m0, s76
	v_lshl_add_u64 v[160:161], v[232:233], 0, s[22:23]
	s_barrier
	ds_read_b128 v[164:167], v177 offset:49152
	ds_read_b128 v[168:171], v177 offset:50176
	ds_read_b128 v[190:193], v177 offset:51200
	ds_read_b128 v[194:197], v177 offset:52224
	ds_read_b128 v[198:201], v177 offset:53248
	ds_read_b128 v[202:205], v177 offset:54272
	ds_read_b128 v[206:209], v177 offset:55296
	ds_read_b128 v[210:213], v177 offset:56320
	global_load_lds_dwordx4 v[160:161], off
	s_mov_b32 m0, s77
	v_lshl_add_u64 v[160:161], v[234:235], 0, s[22:23]
	global_load_lds_dwordx4 v[160:161], off
	s_barrier
	s_waitcnt lgkmcnt(0)
	v_mfma_f32_16x16x32_bf16 v[76:79], v[48:51], v[164:167], v[76:79]
	v_mfma_f32_16x16x32_bf16 v[76:79], v[52:55], v[168:171], v[76:79]
	v_mfma_f32_16x16x32_bf16 v[72:75], v[64:67], v[164:167], v[72:75]
	v_mfma_f32_16x16x32_bf16 v[72:75], v[68:71], v[168:171], v[72:75]
	v_mfma_f32_16x16x32_bf16 v[60:63], v[48:51], v[190:193], v[60:63]
	v_mfma_f32_16x16x32_bf16 v[60:63], v[52:55], v[194:197], v[60:63]
	v_mfma_f32_16x16x32_bf16 v[56:59], v[64:67], v[190:193], v[56:59]
	v_mfma_f32_16x16x32_bf16 v[56:59], v[68:71], v[194:197], v[56:59]
	v_mfma_f32_16x16x32_bf16 v[44:47], v[48:51], v[198:201], v[44:47]
	v_mfma_f32_16x16x32_bf16 v[44:47], v[52:55], v[202:205], v[44:47]
	v_mfma_f32_16x16x32_bf16 v[40:43], v[64:67], v[198:201], v[40:43]
	v_mfma_f32_16x16x32_bf16 v[40:43], v[68:71], v[202:205], v[40:43]
	v_mfma_f32_16x16x32_bf16 v[12:15], v[48:51], v[206:209], v[12:15]
	v_mfma_f32_16x16x32_bf16 v[12:15], v[52:55], v[210:213], v[12:15]
	v_mfma_f32_16x16x32_bf16 v[8:11], v[64:67], v[206:209], v[8:11]
	v_mfma_f32_16x16x32_bf16 v[8:11], v[68:71], v[210:213], v[8:11]
	s_barrier
	s_add_u32 s46, s46, 0x100080
	s_addc_u32 s47, s47, 0
	s_add_i32 s41, s48, s51
	s_mov_b32 m0, s41
	v_lshl_add_u64 v[48:49], s[46:47], 0, v[146:147]
	global_load_lds_dwordx4 v[48:49], off
	s_add_i32 m0, s41, 0x2000
	v_lshl_add_u64 v[48:49], s[46:47], 0, v[150:151]
	global_load_lds_dwordx4 v[48:49], off
	s_waitcnt vmcnt(6)
	s_barrier
	v_mfma_f32_16x16x32_bf16 v[16:19], v[214:217], v[164:167], v[16:19]
	v_mfma_f32_16x16x32_bf16 v[68:71], v[218:221], v[168:171], v[16:19]
	v_mfma_f32_16x16x32_bf16 v[16:19], v[222:225], v[164:167], v[20:23]
	v_mfma_f32_16x16x32_bf16 v[64:67], v[226:229], v[168:171], v[16:19]
	v_mfma_f32_16x16x32_bf16 v[16:19], v[214:217], v[190:193], v[32:35]
	v_mfma_f32_16x16x32_bf16 v[52:55], v[218:221], v[194:197], v[16:19]
	v_mfma_f32_16x16x32_bf16 v[16:19], v[222:225], v[190:193], v[36:39]
	v_mfma_f32_16x16x32_bf16 v[48:51], v[226:229], v[194:197], v[16:19]
	v_mfma_f32_16x16x32_bf16 v[16:19], v[214:217], v[198:201], v[28:31]
	v_mfma_f32_16x16x32_bf16 v[28:31], v[218:221], v[202:205], v[16:19]
	v_mfma_f32_16x16x32_bf16 v[16:19], v[222:225], v[198:201], v[24:27]
	v_mfma_f32_16x16x32_bf16 v[24:27], v[226:229], v[202:205], v[16:19]
	v_mfma_f32_16x16x32_bf16 v[4:7], v[214:217], v[206:209], v[4:7]
	v_mfma_f32_16x16x32_bf16 v[4:7], v[218:221], v[210:213], v[4:7]
	v_mfma_f32_16x16x32_bf16 v[0:3], v[222:225], v[206:209], v[0:3]
	v_mfma_f32_16x16x32_bf16 v[0:3], v[226:229], v[210:213], v[0:3]
	s_add_i32 s39, s39, 2
	s_add_u32 s10, s10, 0x100
	s_addc_u32 s11, s11, 0
	s_add_u32 s13, s13, 0x100
	s_addc_u32 s15, s15, 0
	s_cmp_gt_u32 s39, 61
	s_barrier
	s_cbranch_scc0 .LBB0_604
	s_ashr_i32 s4, s12, 4
	s_cmp_eq_u32 s4, 1
	v_lshl_or_b32 v160, s12, 8, v175
	v_mov_b32_e32 v36, 0
	s_cselect_b64 s[46:47], -1, 0
	s_cmp_lg_u32 s4, 1
	v_mov_b32_e32 v37, 0
	v_mov_b32_e32 v38, 0
	v_mov_b32_e32 v39, 0
	v_mov_b32_e32 v32, 0
	v_mov_b32_e32 v33, 0
	v_mov_b32_e32 v34, 0
	v_mov_b32_e32 v35, 0
	v_mov_b32_e32 v20, 0
	v_mov_b32_e32 v21, 0
	v_mov_b32_e32 v22, 0
	v_mov_b32_e32 v23, 0
	v_mov_b32_e32 v16, 0
	v_mov_b32_e32 v17, 0
	v_mov_b32_e32 v18, 0
	v_mov_b32_e32 v19, 0
	s_cbranch_scc1 .LBB0_607
	v_mov_b32_e32 v161, v147
	v_lshl_add_u64 v[16:17], v[160:161], 2, s[18:19]
	v_add_co_u32_e32 v20, vcc, 0xffffc000, v16
	v_lshl_add_u64 v[18:19], v[16:17], 0, s[24:25]
	s_nop 0
	v_addc_co_u32_e32 v21, vcc, -1, v17, vcc
	global_load_dwordx4 v[36:39], v[20:21], off
	global_load_dwordx4 v[32:35], v[18:19], off offset:16
	v_lshl_add_u64 v[18:19], v[16:17], 0, s[26:27]
	v_add_co_u32_e32 v16, vcc, 0xffffd000, v16
	s_nop 1
	v_addc_co_u32_e32 v17, vcc, -1, v17, vcc
	global_load_dwordx4 v[20:23], v[16:17], off offset:-3584
	s_nop 0
	global_load_dwordx4 v[16:19], v[18:19], off offset:16

.LBB0_981:
	ds_read_b128 v[128:131], v163
	ds_read_b128 v[132:135], v163 offset:1024
	ds_read_b128 v[152:155], v163 offset:2048
	ds_read_b128 v[156:159], v163 offset:3072
	s_add_u32 s26, s24, 0xffc00080
	s_addc_u32 s27, s25, -1
	s_cmp_eq_u32 s47, 60
	s_cselect_b32 s29, s15, s27
	s_cselect_b32 s28, s21, s26
	s_cselect_b32 s27, s13, s46
	s_cselect_b32 s26, s44, s45
	v_lshl_add_u64 v[182:183], s[24:25], 0, v[144:145]
	s_add_i32 m0, s23, 0xc000
	ds_read_b128 v[168:171], v164
	ds_read_b128 v[174:177], v164 offset:1024
	ds_read_b128 v[178:181], v164 offset:2048
	ds_read_b128 v[186:189], v164 offset:3072
	ds_read_b128 v[190:193], v164 offset:4096
	ds_read_b128 v[194:197], v164 offset:5120
	ds_read_b128 v[198:201], v164 offset:6144
	ds_read_b128 v[202:205], v164 offset:7168
	global_load_lds_dwordx4 v[182:183], off
	s_add_i32 m0, s23, 0xe000
	v_lshl_add_u64 v[182:183], s[24:25], 0, v[146:147]
	global_load_lds_dwordx4 v[182:183], off
	s_waitcnt lgkmcnt(8)
	s_barrier
	s_waitcnt lgkmcnt(0)
	v_mfma_f32_16x16x32_bf16 v[124:127], v[128:131], v[168:171], v[124:127]
	v_mfma_f32_16x16x32_bf16 v[124:127], v[132:135], v[174:177], v[124:127]
	v_mfma_f32_16x16x32_bf16 v[120:123], v[152:155], v[168:171], v[120:123]
	v_mfma_f32_16x16x32_bf16 v[120:123], v[156:159], v[174:177], v[120:123]
	v_mfma_f32_16x16x32_bf16 v[108:111], v[128:131], v[178:181], v[108:111]
	v_mfma_f32_16x16x32_bf16 v[108:111], v[132:135], v[186:189], v[108:111]
	v_mfma_f32_16x16x32_bf16 v[104:107], v[152:155], v[178:181], v[104:107]
	v_mfma_f32_16x16x32_bf16 v[104:107], v[156:159], v[186:189], v[104:107]
	v_mfma_f32_16x16x32_bf16 v[92:95], v[128:131], v[190:193], v[92:95]
	v_mfma_f32_16x16x32_bf16 v[92:95], v[132:135], v[194:197], v[92:95]
	v_mfma_f32_16x16x32_bf16 v[88:91], v[152:155], v[190:193], v[88:91]
	v_mfma_f32_16x16x32_bf16 v[88:91], v[156:159], v[194:197], v[88:91]
	v_mfma_f32_16x16x32_bf16 v[76:79], v[128:131], v[198:201], v[76:79]
	v_mfma_f32_16x16x32_bf16 v[76:79], v[132:135], v[202:205], v[76:79]
	v_mfma_f32_16x16x32_bf16 v[72:75], v[152:155], v[198:201], v[72:75]
	v_mfma_f32_16x16x32_bf16 v[72:75], v[156:159], v[202:205], v[72:75]
	s_barrier
	s_add_i32 s48, s42, s30
	v_lshl_add_u64 v[182:183], s[26:27], 0, v[138:139]
	s_mov_b32 m0, s48
	ds_read_b128 v[206:209], v165
	ds_read_b128 v[210:213], v165 offset:1024
	ds_read_b128 v[214:217], v165 offset:2048
	ds_read_b128 v[218:221], v165 offset:3072
	global_load_lds_dwordx4 v[182:183], off
	s_add_i32 m0, s48, 0x2000
	v_lshl_add_u64 v[222:223], s[26:27], 0, v[142:143]
	global_load_lds_dwordx4 v[222:223], off
	s_barrier
	s_waitcnt lgkmcnt(0)
	v_mfma_f32_16x16x32_bf16 v[116:119], v[206:209], v[168:171], v[116:119]
	v_mfma_f32_16x16x32_bf16 v[116:119], v[210:213], v[174:177], v[116:119]
	v_mfma_f32_16x16x32_bf16 v[112:115], v[214:217], v[168:171], v[112:115]
	v_mfma_f32_16x16x32_bf16 v[112:115], v[218:221], v[174:177], v[112:115]
	v_mfma_f32_16x16x32_bf16 v[100:103], v[206:209], v[178:181], v[100:103]
	v_mfma_f32_16x16x32_bf16 v[100:103], v[210:213], v[186:189], v[100:103]
	v_mfma_f32_16x16x32_bf16 v[96:99], v[214:217], v[178:181], v[96:99]
	v_mfma_f32_16x16x32_bf16 v[96:99], v[218:221], v[186:189], v[96:99]
	v_mfma_f32_16x16x32_bf16 v[84:87], v[206:209], v[190:193], v[84:87]
	v_mfma_f32_16x16x32_bf16 v[84:87], v[210:213], v[194:197], v[84:87]
	v_mfma_f32_16x16x32_bf16 v[80:83], v[214:217], v[190:193], v[80:83]
	v_mfma_f32_16x16x32_bf16 v[80:83], v[218:221], v[194:197], v[80:83]
	v_mfma_f32_16x16x32_bf16 v[68:71], v[206:209], v[198:201], v[68:71]
	v_mfma_f32_16x16x32_bf16 v[68:71], v[210:213], v[202:205], v[68:71]
	v_mfma_f32_16x16x32_bf16 v[64:67], v[214:217], v[198:201], v[64:67]
	v_mfma_f32_16x16x32_bf16 v[64:67], v[218:221], v[202:205], v[64:67]
	s_mov_b32 m0, s23
	v_lshl_add_u64 v[224:225], s[28:29], 0, v[136:137]
	s_barrier
	ds_read_b128 v[168:171], v164 offset:16384
	ds_read_b128 v[174:177], v164 offset:17408
	ds_read_b128 v[178:181], v164 offset:18432
	ds_read_b128 v[186:189], v164 offset:19456
	ds_read_b128 v[190:193], v164 offset:20480
	ds_read_b128 v[194:197], v164 offset:21504
	ds_read_b128 v[198:201], v164 offset:22528
	ds_read_b128 v[202:205], v164 offset:23552
	global_load_lds_dwordx4 v[224:225], off
	s_mov_b32 m0, s31
	v_lshl_add_u64 v[226:227], s[28:29], 0, v[140:141]
	global_load_lds_dwordx4 v[226:227], off
	s_barrier
	s_waitcnt lgkmcnt(0)
	v_mfma_f32_16x16x32_bf16 v[60:63], v[128:131], v[168:171], v[60:63]
	v_mfma_f32_16x16x32_bf16 v[60:63], v[132:135], v[174:177], v[60:63]
	v_mfma_f32_16x16x32_bf16 v[56:59], v[152:155], v[168:171], v[56:59]
	v_mfma_f32_16x16x32_bf16 v[56:59], v[156:159], v[174:177], v[56:59]
	v_mfma_f32_16x16x32_bf16 v[44:47], v[128:131], v[178:181], v[44:47]
	v_mfma_f32_16x16x32_bf16 v[44:47], v[132:135], v[186:189], v[44:47]
	v_mfma_f32_16x16x32_bf16 v[40:43], v[152:155], v[178:181], v[40:43]
	v_mfma_f32_16x16x32_bf16 v[40:43], v[156:159], v[186:189], v[40:43]
	v_mfma_f32_16x16x32_bf16 v[28:31], v[128:131], v[190:193], v[28:31]
	v_mfma_f32_16x16x32_bf16 v[28:31], v[132:135], v[194:197], v[28:31]
	v_mfma_f32_16x16x32_bf16 v[24:27], v[152:155], v[190:193], v[24:27]
	v_mfma_f32_16x16x32_bf16 v[24:27], v[156:159], v[194:197], v[24:27]
	v_mfma_f32_16x16x32_bf16 v[12:15], v[128:131], v[198:201], v[12:15]
	v_mfma_f32_16x16x32_bf16 v[12:15], v[132:135], v[202:205], v[12:15]
	v_mfma_f32_16x16x32_bf16 v[8:11], v[152:155], v[198:201], v[8:11]
	v_mfma_f32_16x16x32_bf16 v[8:11], v[156:159], v[202:205], v[8:11]
	s_barrier
	s_add_u32 s48, s26, 0x100000
	s_addc_u32 s49, s27, 0
	s_add_i32 s50, s43, s30
	s_mov_b32 m0, s50
	v_lshl_add_u64 v[128:129], s[48:49], 0, v[138:139]
	global_load_lds_dwordx4 v[128:129], off
	s_add_i32 m0, s50, 0x2000
	v_lshl_add_u64 v[128:129], s[48:49], 0, v[142:143]
	global_load_lds_dwordx4 v[128:129], off
	s_waitcnt vmcnt(6)
	s_barrier
	v_mfma_f32_16x16x32_bf16 v[52:55], v[206:209], v[168:171], v[52:55]
	v_mfma_f32_16x16x32_bf16 v[52:55], v[210:213], v[174:177], v[52:55]
	v_mfma_f32_16x16x32_bf16 v[48:51], v[214:217], v[168:171], v[48:51]
	v_mfma_f32_16x16x32_bf16 v[48:51], v[218:221], v[174:177], v[48:51]
	v_mfma_f32_16x16x32_bf16 v[36:39], v[206:209], v[178:181], v[36:39]
	v_mfma_f32_16x16x32_bf16 v[36:39], v[210:213], v[186:189], v[36:39]
	v_mfma_f32_16x16x32_bf16 v[32:35], v[214:217], v[178:181], v[32:35]
	v_mfma_f32_16x16x32_bf16 v[32:35], v[218:221], v[186:189], v[32:35]
	v_mfma_f32_16x16x32_bf16 v[20:23], v[206:209], v[190:193], v[20:23]
	v_mfma_f32_16x16x32_bf16 v[20:23], v[210:213], v[194:197], v[20:23]
	v_mfma_f32_16x16x32_bf16 v[16:19], v[214:217], v[190:193], v[16:19]
	v_mfma_f32_16x16x32_bf16 v[16:19], v[218:221], v[194:197], v[16:19]
	v_mfma_f32_16x16x32_bf16 v[4:7], v[206:209], v[198:201], v[4:7]
	v_mfma_f32_16x16x32_bf16 v[4:7], v[210:213], v[202:205], v[4:7]
	v_mfma_f32_16x16x32_bf16 v[0:3], v[214:217], v[198:201], v[0:3]
	v_mfma_f32_16x16x32_bf16 v[0:3], v[218:221], v[202:205], v[0:3]
	s_add_i32 s48, 0, 0x18000
	v_add_u32_e32 v156, s48, v161
	s_barrier
	ds_read_b128 v[128:131], v156
	ds_read_b128 v[132:135], v156 offset:1024
	ds_read_b128 v[152:155], v156 offset:2048
	ds_read_b128 v[156:159], v156 offset:3072
	s_add_u32 s28, s28, 0x400000
	s_addc_u32 s29, s29, 0
	s_mov_b32 m0, s34
	v_lshl_add_u64 v[206:207], s[28:29], 0, v[136:137]
	ds_read_b128 v[168:171], v164 offset:32768
	ds_read_b128 v[174:177], v164 offset:33792
	ds_read_b128 v[178:181], v164 offset:34816
	ds_read_b128 v[186:189], v164 offset:35840
	ds_read_b128 v[190:193], v164 offset:36864
	ds_read_b128 v[194:197], v164 offset:37888
	ds_read_b128 v[198:201], v164 offset:38912
	ds_read_b128 v[202:205], v164 offset:39936
	global_load_lds_dwordx4 v[206:207], off
	s_mov_b32 m0, s35
	v_lshl_add_u64 v[206:207], s[28:29], 0, v[140:141]
	global_load_lds_dwordx4 v[206:207], off
	s_waitcnt lgkmcnt(8)
	s_barrier
	s_waitcnt lgkmcnt(0)
	v_mfma_f32_16x16x32_bf16 v[124:127], v[128:131], v[168:171], v[124:127]
	v_mfma_f32_16x16x32_bf16 v[124:127], v[132:135], v[174:177], v[124:127]
	v_mfma_f32_16x16x32_bf16 v[120:123], v[152:155], v[168:171], v[120:123]
	v_mfma_f32_16x16x32_bf16 v[120:123], v[156:159], v[174:177], v[120:123]
	v_mfma_f32_16x16x32_bf16 v[108:111], v[128:131], v[178:181], v[108:111]
	v_mfma_f32_16x16x32_bf16 v[108:111], v[132:135], v[186:189], v[108:111]
	v_mfma_f32_16x16x32_bf16 v[104:107], v[152:155], v[178:181], v[104:107]
	v_mfma_f32_16x16x32_bf16 v[104:107], v[156:159], v[186:189], v[104:107]
	v_mfma_f32_16x16x32_bf16 v[92:95], v[128:131], v[190:193], v[92:95]
	v_mfma_f32_16x16x32_bf16 v[92:95], v[132:135], v[194:197], v[92:95]
	v_mfma_f32_16x16x32_bf16 v[88:91], v[152:155], v[190:193], v[88:91]
	v_mfma_f32_16x16x32_bf16 v[88:91], v[156:159], v[194:197], v[88:91]
	v_mfma_f32_16x16x32_bf16 v[76:79], v[128:131], v[198:201], v[76:79]
	v_mfma_f32_16x16x32_bf16 v[76:79], v[132:135], v[202:205], v[76:79]
	v_mfma_f32_16x16x32_bf16 v[72:75], v[152:155], v[198:201], v[72:75]
	v_mfma_f32_16x16x32_bf16 v[72:75], v[156:159], v[202:205], v[72:75]
	s_barrier
	s_add_i32 s28, 0, 0x1c000
	s_add_i32 s29, s48, s30
	v_add_u32_e32 v167, s28, v161
	v_lshl_add_u64 v[182:183], v[182:183], 0, s[10:11]
	s_mov_b32 m0, s29
	ds_read_b128 v[206:209], v167
	ds_read_b128 v[210:213], v167 offset:1024
	ds_read_b128 v[214:217], v167 offset:2048
	ds_read_b128 v[218:221], v167 offset:3072
	global_load_lds_dwordx4 v[182:183], off
	s_add_i32 m0, s29, 0x2000
	v_lshl_add_u64 v[182:183], v[222:223], 0, s[10:11]
	global_load_lds_dwordx4 v[182:183], off
	s_barrier
	s_waitcnt lgkmcnt(0)
	v_mfma_f32_16x16x32_bf16 v[116:119], v[206:209], v[168:171], v[116:119]
	v_mfma_f32_16x16x32_bf16 v[116:119], v[210:213], v[174:177], v[116:119]
	v_mfma_f32_16x16x32_bf16 v[112:115], v[214:217], v[168:171], v[112:115]
	v_mfma_f32_16x16x32_bf16 v[112:115], v[218:221], v[174:177], v[112:115]
	v_mfma_f32_16x16x32_bf16 v[100:103], v[206:209], v[178:181], v[100:103]
	v_mfma_f32_16x16x32_bf16 v[100:103], v[210:213], v[186:189], v[100:103]
	v_mfma_f32_16x16x32_bf16 v[96:99], v[214:217], v[178:181], v[96:99]
	v_mfma_f32_16x16x32_bf16 v[96:99], v[218:221], v[186:189], v[96:99]
	v_mfma_f32_16x16x32_bf16 v[84:87], v[206:209], v[190:193], v[84:87]
	v_mfma_f32_16x16x32_bf16 v[84:87], v[210:213], v[194:197], v[84:87]
	v_mfma_f32_16x16x32_bf16 v[80:83], v[214:217], v[190:193], v[80:83]
	v_mfma_f32_16x16x32_bf16 v[80:83], v[218:221], v[194:197], v[80:83]
	v_mfma_f32_16x16x32_bf16 v[68:71], v[206:209], v[198:201], v[68:71]
	v_mfma_f32_16x16x32_bf16 v[68:71], v[210:213], v[202:205], v[68:71]
	v_mfma_f32_16x16x32_bf16 v[64:67], v[214:217], v[198:201], v[64:67]
	v_mfma_f32_16x16x32_bf16 v[64:67], v[218:221], v[202:205], v[64:67]
	s_mov_b32 m0, s37
	v_lshl_add_u64 v[182:183], v[224:225], 0, s[10:11]
	s_barrier
	ds_read_b128 v[168:171], v164 offset:49152
	ds_read_b128 v[174:177], v164 offset:50176
	ds_read_b128 v[178:181], v164 offset:51200
	ds_read_b128 v[186:189], v164 offset:52224
	ds_read_b128 v[190:193], v164 offset:53248
	ds_read_b128 v[194:197], v164 offset:54272
	ds_read_b128 v[198:201], v164 offset:55296
	ds_read_b128 v[202:205], v164 offset:56320
	global_load_lds_dwordx4 v[182:183], off
	s_mov_b32 m0, s38
	v_lshl_add_u64 v[182:183], v[226:227], 0, s[10:11]
	global_load_lds_dwordx4 v[182:183], off
	s_barrier
	s_waitcnt lgkmcnt(0)
	v_mfma_f32_16x16x32_bf16 v[60:63], v[128:131], v[168:171], v[60:63]
	v_mfma_f32_16x16x32_bf16 v[60:63], v[132:135], v[174:177], v[60:63]
	v_mfma_f32_16x16x32_bf16 v[56:59], v[152:155], v[168:171], v[56:59]
	v_mfma_f32_16x16x32_bf16 v[56:59], v[156:159], v[174:177], v[56:59]
	v_mfma_f32_16x16x32_bf16 v[44:47], v[128:131], v[178:181], v[44:47]
	v_mfma_f32_16x16x32_bf16 v[44:47], v[132:135], v[186:189], v[44:47]
	v_mfma_f32_16x16x32_bf16 v[40:43], v[152:155], v[178:181], v[40:43]
	v_mfma_f32_16x16x32_bf16 v[40:43], v[156:159], v[186:189], v[40:43]
	v_mfma_f32_16x16x32_bf16 v[28:31], v[128:131], v[190:193], v[28:31]
	v_mfma_f32_16x16x32_bf16 v[28:31], v[132:135], v[194:197], v[28:31]
	v_mfma_f32_16x16x32_bf16 v[24:27], v[152:155], v[190:193], v[24:27]
	v_mfma_f32_16x16x32_bf16 v[24:27], v[156:159], v[194:197], v[24:27]
	v_mfma_f32_16x16x32_bf16 v[12:15], v[128:131], v[198:201], v[12:15]
	v_mfma_f32_16x16x32_bf16 v[12:15], v[132:135], v[202:205], v[12:15]
	v_mfma_f32_16x16x32_bf16 v[8:11], v[152:155], v[198:201], v[8:11]
	v_mfma_f32_16x16x32_bf16 v[8:11], v[156:159], v[202:205], v[8:11]
	s_barrier
	s_add_u32 s26, s26, 0x100080
	s_addc_u32 s27, s27, 0
	s_add_i32 s28, s28, s30
	s_mov_b32 m0, s28
	v_lshl_add_u64 v[128:129], s[26:27], 0, v[138:139]
	global_load_lds_dwordx4 v[128:129], off
	s_add_i32 m0, s28, 0x2000
	v_lshl_add_u64 v[128:129], s[26:27], 0, v[142:143]
	global_load_lds_dwordx4 v[128:129], off
	s_waitcnt vmcnt(6)
	s_barrier
	v_mfma_f32_16x16x32_bf16 v[52:55], v[206:209], v[168:171], v[52:55]
	v_mfma_f32_16x16x32_bf16 v[52:55], v[210:213], v[174:177], v[52:55]
	v_mfma_f32_16x16x32_bf16 v[48:51], v[214:217], v[168:171], v[48:51]
	v_mfma_f32_16x16x32_bf16 v[48:51], v[218:221], v[174:177], v[48:51]
	v_mfma_f32_16x16x32_bf16 v[36:39], v[206:209], v[178:181], v[36:39]
	v_mfma_f32_16x16x32_bf16 v[36:39], v[210:213], v[186:189], v[36:39]
	v_mfma_f32_16x16x32_bf16 v[32:35], v[214:217], v[178:181], v[32:35]
	v_mfma_f32_16x16x32_bf16 v[32:35], v[218:221], v[186:189], v[32:35]
	v_mfma_f32_16x16x32_bf16 v[20:23], v[206:209], v[190:193], v[20:23]
	v_mfma_f32_16x16x32_bf16 v[20:23], v[210:213], v[194:197], v[20:23]
	v_mfma_f32_16x16x32_bf16 v[16:19], v[214:217], v[190:193], v[16:19]
	v_mfma_f32_16x16x32_bf16 v[16:19], v[218:221], v[194:197], v[16:19]
	v_mfma_f32_16x16x32_bf16 v[4:7], v[206:209], v[198:201], v[4:7]
	v_mfma_f32_16x16x32_bf16 v[4:7], v[210:213], v[202:205], v[4:7]
	v_mfma_f32_16x16x32_bf16 v[0:3], v[214:217], v[198:201], v[0:3]
	v_mfma_f32_16x16x32_bf16 v[0:3], v[218:221], v[202:205], v[0:3]
	s_add_i32 s47, s47, 2
	s_add_u32 s24, s24, 0x100
	s_addc_u32 s25, s25, 0
	s_add_u32 s45, s45, 0x100
	s_addc_u32 s46, s46, 0
	s_cmp_gt_u32 s47, 61
	s_barrier
	s_cbranch_scc0 .LBB0_981
	v_lshl_add_u32 v156, s20, 8, v160
	v_lshl_or_b32 v152, s22, 8, v162
	v_ashrrev_i32_e32 v157, 31, v156
	v_ashrrev_i32_e32 v153, 31, v152
	v_lshlrev_b64 v[128:129], 13, v[156:157]
	v_lshl_add_u64 v[128:129], s[56:57], 0, v[128:129]
	v_lshlrev_b64 v[154:155], 1, v[152:153]
	v_lshl_add_u64 v[128:129], v[128:129], 0, v[154:155]
	global_load_dwordx4 v[168:171], v[128:129], off
	global_load_dwordx4 v[174:177], v[128:129], off offset:256
	v_or_b32_e32 v158, 16, v156
	v_ashrrev_i32_e32 v159, 31, v158
	v_lshlrev_b64 v[128:129], 13, v[158:159]
	v_lshl_add_u64 v[128:129], s[56:57], 0, v[128:129]
	v_lshl_add_u64 v[128:129], v[128:129], 0, v[154:155]
	global_load_dwordx4 v[132:135], v[128:129], off
	s_nop 0
	global_load_dwordx4 v[128:131], v[128:129], off offset:256
	v_and_b32_e32 v173, 64, v166
	v_xor_b32_e32 v167, 16, v166
	v_add_u32_e32 v173, 64, v173
	v_xor_b32_e32 v180, 32, v166
	v_cmp_lt_i32_e32 vcc, v167, v173
	v_lshlrev_b64 v[178:179], 15, v[156:157]
	v_lshl_add_u64 v[178:179], s[68:69], 0, v[178:179]
	v_cndmask_b32_e32 v167, v166, v167, vcc
	v_cmp_lt_i32_e32 vcc, v180, v173
	v_lshlrev_b32_e32 v167, 2, v167
	v_lshl_add_u64 v[178:179], v[178:179], 0, v[154:155]
	v_cndmask_b32_e32 v173, v166, v180, vcc
	s_waitcnt vmcnt(0)
	v_lshlrev_b32_e32 v180, 16, v168
	v_and_b32_e32 v181, 0xffff0000, v168
	v_lshlrev_b32_e32 v168, 16, v169
	v_and_b32_e32 v169, 0xffff0000, v169
	v_lshlrev_b32_e32 v186, 16, v174
	v_and_b32_e32 v187, 0xffff0000, v174
	v_lshlrev_b32_e32 v174, 16, v175
	v_and_b32_e32 v175, 0xffff0000, v175
	v_lshlrev_b32_e32 v182, 16, v170
	v_and_b32_e32 v183, 0xffff0000, v170
	v_lshlrev_b32_e32 v170, 16, v171
	v_and_b32_e32 v171, 0xffff0000, v171
	v_lshlrev_b32_e32 v188, 16, v176
	v_and_b32_e32 v189, 0xffff0000, v176
	v_lshlrev_b32_e32 v176, 16, v177
	v_and_b32_e32 v177, 0xffff0000, v177
	v_pk_add_f32 v[126:127], v[126:127], v[168:169]
	v_pk_add_f32 v[124:125], v[124:125], v[180:181]
	v_pk_add_f32 v[118:119], v[118:119], v[174:175]
	v_pk_add_f32 v[116:117], v[116:117], v[186:187]
	v_pk_add_f32 v[122:123], v[122:123], v[170:171]
	v_pk_add_f32 v[120:121], v[120:121], v[182:183]
	v_pk_add_f32 v[168:169], v[114:115], v[176:177]
	v_pk_add_f32 v[170:171], v[112:113], v[188:189]
	v_mul_f32_e32 v114, v125, v125
	v_mul_f32_e32 v115, v127, v127
	v_cvt_pk_bf16_f32 v112, v124, v125
	v_cvt_pk_bf16_f32 v113, v126, v127
	v_mul_f32_e32 v125, v117, v117
	v_mul_f32_e32 v127, v119, v119
	v_mul_f32_e32 v174, v121, v121
	v_mul_f32_e32 v176, v171, v171
	v_fmac_f32_e32 v114, v124, v124
	v_fmac_f32_e32 v115, v126, v126
	v_fmac_f32_e32 v125, v116, v116
	v_fmac_f32_e32 v127, v118, v118
	v_mul_f32_e32 v175, v123, v123
	v_mul_f32_e32 v177, v169, v169
	v_fmac_f32_e32 v174, v120, v120
	v_fmac_f32_e32 v176, v170, v170
	v_add_f32_e32 v114, v114, v115
	v_add_f32_e32 v115, v125, v127
	v_fmac_f32_e32 v175, v122, v122
	v_fmac_f32_e32 v177, v168, v168
	v_add_f32_e32 v114, v174, v114
	v_add_f32_e32 v115, v176, v115
	v_add_f32_e32 v114, v175, v114
	v_add_f32_e32 v115, v177, v115
	v_add_f32_e32 v124, v114, v115
	ds_bpermute_b32 v125, v167, v124
	v_cvt_pk_bf16_f32 v114, v120, v121
	v_cvt_pk_bf16_f32 v115, v122, v123
	global_store_dwordx4 v[178:179], v[112:115], off
	v_lshlrev_b32_e32 v122, 2, v173
	s_waitcnt lgkmcnt(0)
	v_add_f32_e32 v112, v124, v125
	ds_bpermute_b32 v113, v122, v112
	v_cvt_pk_bf16_f32 v114, v116, v117
	v_cvt_pk_bf16_f32 v115, v118, v119
	v_cvt_pk_bf16_f32 v116, v170, v171
	v_cvt_pk_bf16_f32 v117, v168, v169
	global_store_dwordx4 v[178:179], v[114:117], off offset:256
	s_and_saveexec_b64 s[20:21], s[6:7]
	s_cbranch_execz .LBB0_984
	v_lshl_add_u64 v[114:115], v[156:157], 2, s[72:73]
	s_waitcnt lgkmcnt(0)
	v_add_f32_e32 v112, v112, v113
	global_atomic_add_f32 v[114:115], v112, off
